# GEMM K-loops: first iteration peeled with C=0 MFMAs, accumulator zero-init removed (all 7 instantiations)
# speedup vs baseline: 1.0111x; 1.0111x over previous
.LBB0_453:
	s_add_u32 s2, s2, 0x40080
	s_addc_u32 s3, s3, 0
	s_add_u32 s6, s0, 0x100
	s_addc_u32 s7, s1, 0
	s_mov_b32 s8, -2
	s_mov_b64 s[58:59], 0x80
	s_add_u32 s0, s2, 0xfffc0080
	s_addc_u32 s1, s3, -1
	s_add_i32 s9, 0, 0x10000
	s_cmp_eq_u32 s8, 12
	s_cselect_b32 s5, s47, s1
	s_cselect_b32 s4, s46, s0
	s_cselect_b32 s1, s49, s7
	s_cselect_b32 s0, s48, s6
	s_add_i32 s33, 0, 0x14000
	v_add_u32_e32 v140, s9, v166
	v_add_u32_e32 v168, s33, v166
	ds_read_b128 v[112:115], v140
	ds_read_b128 v[132:135], v140 offset:1024
	ds_read_b128 v[136:139], v140 offset:2048
	ds_read_b128 v[140:143], v140 offset:3072
	ds_read_b128 v[144:147], v168
	ds_read_b128 v[148:151], v168 offset:1024
	ds_read_b128 v[162:165], v168 offset:2048
	ds_read_b128 v[168:171], v168 offset:3072
	v_lshl_add_u64 v[200:201], s[2:3], 0, v[158:159]
	s_add_i32 m0, s21, 0xc000
	ds_read_b128 v[172:175], v167
	ds_read_b128 v[184:187], v167 offset:1024
	ds_read_b128 v[188:191], v167 offset:2048
	ds_read_b128 v[192:195], v167 offset:3072
	ds_read_b128 v[196:199], v167 offset:4096
	ds_read_b128 v[214:217], v167 offset:5120
	ds_read_b128 v[218:221], v167 offset:6144
	ds_read_b128 v[222:225], v167 offset:7168
	global_load_lds_dwordx4 v[200:201], off
	v_lshl_add_u64 v[200:201], s[2:3], 0, v[160:161]
	s_add_i32 m0, s21, 0xe000
	s_nop 0
	global_load_lds_dwordx4 v[200:201], off
	s_waitcnt vmcnt(8)
	s_waitcnt lgkmcnt(0)
	s_barrier
	s_setprio 1
	s_waitcnt lgkmcnt(0)
	v_mfma_f32_16x16x32_bf16 v[128:131], v[112:115], v[172:175], 0
	v_mfma_f32_16x16x32_bf16 v[124:127], v[136:139], v[172:175], 0
	v_mfma_f32_16x16x32_bf16 v[108:111], v[112:115], v[188:191], 0
	v_mfma_f32_16x16x32_bf16 v[104:107], v[136:139], v[188:191], 0
	v_mfma_f32_16x16x32_bf16 v[92:95], v[112:115], v[196:199], 0
	v_mfma_f32_16x16x32_bf16 v[88:91], v[136:139], v[196:199], 0
	v_mfma_f32_16x16x32_bf16 v[76:79], v[112:115], v[218:221], 0
	v_mfma_f32_16x16x32_bf16 v[72:75], v[136:139], v[218:221], 0
	v_mfma_f32_16x16x32_bf16 v[128:131], v[132:135], v[184:187], v[128:131]
	v_mfma_f32_16x16x32_bf16 v[124:127], v[140:143], v[184:187], v[124:127]
	v_mfma_f32_16x16x32_bf16 v[108:111], v[132:135], v[192:195], v[108:111]
	v_mfma_f32_16x16x32_bf16 v[104:107], v[140:143], v[192:195], v[104:107]
	v_mfma_f32_16x16x32_bf16 v[92:95], v[132:135], v[214:217], v[92:95]
	v_mfma_f32_16x16x32_bf16 v[88:91], v[140:143], v[214:217], v[88:91]
	v_mfma_f32_16x16x32_bf16 v[76:79], v[132:135], v[222:225], v[76:79]
	v_mfma_f32_16x16x32_bf16 v[72:75], v[140:143], v[222:225], v[72:75]
	s_setprio 0
	s_setprio 1
	v_mfma_f32_16x16x32_bf16 v[120:123], v[144:147], v[172:175], 0
	v_mfma_f32_16x16x32_bf16 v[116:119], v[162:165], v[172:175], 0
	v_mfma_f32_16x16x32_bf16 v[100:103], v[144:147], v[188:191], 0
	v_mfma_f32_16x16x32_bf16 v[96:99], v[162:165], v[188:191], 0
	v_mfma_f32_16x16x32_bf16 v[84:87], v[144:147], v[196:199], 0
	v_mfma_f32_16x16x32_bf16 v[80:83], v[162:165], v[196:199], 0
	v_mfma_f32_16x16x32_bf16 v[68:71], v[144:147], v[218:221], 0
	v_mfma_f32_16x16x32_bf16 v[64:67], v[162:165], v[218:221], 0
	v_mfma_f32_16x16x32_bf16 v[120:123], v[148:151], v[184:187], v[120:123]
	v_mfma_f32_16x16x32_bf16 v[116:119], v[168:171], v[184:187], v[116:119]
	v_mfma_f32_16x16x32_bf16 v[100:103], v[148:151], v[192:195], v[100:103]
	v_mfma_f32_16x16x32_bf16 v[96:99], v[168:171], v[192:195], v[96:99]
	v_mfma_f32_16x16x32_bf16 v[84:87], v[148:151], v[214:217], v[84:87]
	v_mfma_f32_16x16x32_bf16 v[80:83], v[168:171], v[214:217], v[80:83]
	v_mfma_f32_16x16x32_bf16 v[68:71], v[148:151], v[222:225], v[68:71]
	v_mfma_f32_16x16x32_bf16 v[64:67], v[168:171], v[222:225], v[64:67]
	s_setprio 0
	s_barrier
	s_add_i32 s9, s9, s13
	v_lshl_add_u64 v[200:201], s[0:1], 0, v[176:177]
	s_mov_b32 m0, s9
	ds_read_b128 v[172:175], v167 offset:16384
	ds_read_b128 v[184:187], v167 offset:17408
	ds_read_b128 v[188:191], v167 offset:18432
	ds_read_b128 v[192:195], v167 offset:19456
	ds_read_b128 v[196:199], v167 offset:20480
	ds_read_b128 v[214:217], v167 offset:21504
	ds_read_b128 v[218:221], v167 offset:22528
	ds_read_b128 v[222:225], v167 offset:23552
	global_load_lds_dwordx4 v[200:201], off
	s_add_i32 m0, s9, 0x2000
	s_add_u32 s36, s0, 0x40000
	v_lshl_add_u64 v[226:227], s[0:1], 0, v[156:157]
	s_addc_u32 s37, s1, 0
	s_add_i32 s9, s33, s13
	global_load_lds_dwordx4 v[226:227], off
	v_lshl_add_u64 v[228:229], s[36:37], 0, v[176:177]
	s_mov_b32 m0, s9
	v_lshl_add_u64 v[230:231], s[4:5], 0, v[154:155]
	global_load_lds_dwordx4 v[228:229], off
	v_lshl_add_u64 v[228:229], s[36:37], 0, v[156:157]
	s_add_i32 m0, s9, 0x2000
	s_nop 0
	global_load_lds_dwordx4 v[228:229], off
	v_lshl_add_u64 v[228:229], s[4:5], 0, v[152:153]
	s_mov_b32 m0, s21
	s_nop 0
	global_load_lds_dwordx4 v[228:229], off
	s_mov_b32 m0, s23
	s_nop 0
	global_load_lds_dwordx4 v[230:231], off
	s_waitcnt vmcnt(8)
	s_waitcnt lgkmcnt(0)
	s_barrier
	s_setprio 1
	s_waitcnt lgkmcnt(0)
	v_mfma_f32_16x16x32_bf16 v[60:63], v[112:115], v[172:175], 0
	v_mfma_f32_16x16x32_bf16 v[56:59], v[136:139], v[172:175], 0
	v_mfma_f32_16x16x32_bf16 v[44:47], v[112:115], v[188:191], 0
	v_mfma_f32_16x16x32_bf16 v[40:43], v[136:139], v[188:191], 0
	v_mfma_f32_16x16x32_bf16 v[28:31], v[112:115], v[196:199], 0
	v_mfma_f32_16x16x32_bf16 v[24:27], v[136:139], v[196:199], 0
	v_mfma_f32_16x16x32_bf16 v[12:15], v[112:115], v[218:221], 0
	v_mfma_f32_16x16x32_bf16 v[8:11], v[136:139], v[218:221], 0
	v_mfma_f32_16x16x32_bf16 v[60:63], v[132:135], v[184:187], v[60:63]
	v_mfma_f32_16x16x32_bf16 v[56:59], v[140:143], v[184:187], v[56:59]
	v_mfma_f32_16x16x32_bf16 v[44:47], v[132:135], v[192:195], v[44:47]
	v_mfma_f32_16x16x32_bf16 v[40:43], v[140:143], v[192:195], v[40:43]
	v_mfma_f32_16x16x32_bf16 v[28:31], v[132:135], v[214:217], v[28:31]
	v_mfma_f32_16x16x32_bf16 v[24:27], v[140:143], v[214:217], v[24:27]
	v_mfma_f32_16x16x32_bf16 v[12:15], v[132:135], v[222:225], v[12:15]
	v_mfma_f32_16x16x32_bf16 v[8:11], v[140:143], v[222:225], v[8:11]
	s_setprio 0
	s_setprio 1
	v_mfma_f32_16x16x32_bf16 v[52:55], v[144:147], v[172:175], 0
	v_mfma_f32_16x16x32_bf16 v[48:51], v[162:165], v[172:175], 0
	v_mfma_f32_16x16x32_bf16 v[36:39], v[144:147], v[188:191], 0
	v_mfma_f32_16x16x32_bf16 v[32:35], v[162:165], v[188:191], 0
	v_mfma_f32_16x16x32_bf16 v[20:23], v[144:147], v[196:199], 0
	v_mfma_f32_16x16x32_bf16 v[16:19], v[162:165], v[196:199], 0
	v_mfma_f32_16x16x32_bf16 v[4:7], v[144:147], v[218:221], 0
	v_mfma_f32_16x16x32_bf16 v[0:3], v[162:165], v[218:221], 0
	v_mfma_f32_16x16x32_bf16 v[52:55], v[148:151], v[184:187], v[52:55]
	v_mfma_f32_16x16x32_bf16 v[48:51], v[168:171], v[184:187], v[48:51]
	v_mfma_f32_16x16x32_bf16 v[36:39], v[148:151], v[192:195], v[36:39]
	v_mfma_f32_16x16x32_bf16 v[32:35], v[168:171], v[192:195], v[32:35]
	v_mfma_f32_16x16x32_bf16 v[20:23], v[148:151], v[214:217], v[20:23]
	v_mfma_f32_16x16x32_bf16 v[16:19], v[168:171], v[214:217], v[16:19]
	v_mfma_f32_16x16x32_bf16 v[4:7], v[148:151], v[222:225], v[4:7]
	v_mfma_f32_16x16x32_bf16 v[0:3], v[168:171], v[222:225], v[0:3]
	s_setprio 0
	s_barrier
	s_add_i32 s9, 0, 0x18000
	s_add_i32 s33, 0, 0x1c000
	v_add_u32_e32 v140, s9, v166
	v_add_u32_e32 v168, s33, v166
	ds_read_b128 v[112:115], v140
	ds_read_b128 v[132:135], v140 offset:1024
	ds_read_b128 v[136:139], v140 offset:2048
	ds_read_b128 v[140:143], v140 offset:3072
	ds_read_b128 v[144:147], v168
	ds_read_b128 v[148:151], v168 offset:1024
	ds_read_b128 v[162:165], v168 offset:2048
	ds_read_b128 v[168:171], v168 offset:3072
	s_add_u32 s4, s4, 0x40000
	s_addc_u32 s5, s5, 0
	s_mov_b32 m0, s52
	v_lshl_add_u64 v[232:233], s[4:5], 0, v[152:153]
	ds_read_b128 v[172:175], v167 offset:32768
	ds_read_b128 v[184:187], v167 offset:33792
	ds_read_b128 v[188:191], v167 offset:34816
	ds_read_b128 v[192:195], v167 offset:35840
	ds_read_b128 v[196:199], v167 offset:36864
	ds_read_b128 v[214:217], v167 offset:37888
	ds_read_b128 v[218:221], v167 offset:38912
	ds_read_b128 v[222:225], v167 offset:39936
	global_load_lds_dwordx4 v[232:233], off
	v_lshl_add_u64 v[232:233], s[4:5], 0, v[154:155]
	s_mov_b32 m0, s53
	s_nop 0
	global_load_lds_dwordx4 v[232:233], off
	s_waitcnt vmcnt(8)
	s_waitcnt lgkmcnt(0)
	s_barrier
	s_setprio 1
	s_waitcnt lgkmcnt(0)
	v_mfma_f32_16x16x32_bf16 v[128:131], v[112:115], v[172:175], v[128:131]
	v_mfma_f32_16x16x32_bf16 v[124:127], v[136:139], v[172:175], v[124:127]
	v_mfma_f32_16x16x32_bf16 v[108:111], v[112:115], v[188:191], v[108:111]
	v_mfma_f32_16x16x32_bf16 v[104:107], v[136:139], v[188:191], v[104:107]
	v_mfma_f32_16x16x32_bf16 v[92:95], v[112:115], v[196:199], v[92:95]
	v_mfma_f32_16x16x32_bf16 v[88:91], v[136:139], v[196:199], v[88:91]
	v_mfma_f32_16x16x32_bf16 v[76:79], v[112:115], v[218:221], v[76:79]
	v_mfma_f32_16x16x32_bf16 v[72:75], v[136:139], v[218:221], v[72:75]
	v_mfma_f32_16x16x32_bf16 v[128:131], v[132:135], v[184:187], v[128:131]
	v_mfma_f32_16x16x32_bf16 v[124:127], v[140:143], v[184:187], v[124:127]
	v_mfma_f32_16x16x32_bf16 v[108:111], v[132:135], v[192:195], v[108:111]
	v_mfma_f32_16x16x32_bf16 v[104:107], v[140:143], v[192:195], v[104:107]
	v_mfma_f32_16x16x32_bf16 v[92:95], v[132:135], v[214:217], v[92:95]
	v_mfma_f32_16x16x32_bf16 v[88:91], v[140:143], v[214:217], v[88:91]
	v_mfma_f32_16x16x32_bf16 v[76:79], v[132:135], v[222:225], v[76:79]
	v_mfma_f32_16x16x32_bf16 v[72:75], v[140:143], v[222:225], v[72:75]
	s_setprio 0
	s_setprio 1
	v_mfma_f32_16x16x32_bf16 v[120:123], v[144:147], v[172:175], v[120:123]
	v_mfma_f32_16x16x32_bf16 v[116:119], v[162:165], v[172:175], v[116:119]
	v_mfma_f32_16x16x32_bf16 v[100:103], v[144:147], v[188:191], v[100:103]
	v_mfma_f32_16x16x32_bf16 v[96:99], v[162:165], v[188:191], v[96:99]
	v_mfma_f32_16x16x32_bf16 v[84:87], v[144:147], v[196:199], v[84:87]
	v_mfma_f32_16x16x32_bf16 v[80:83], v[162:165], v[196:199], v[80:83]
	v_mfma_f32_16x16x32_bf16 v[68:71], v[144:147], v[218:221], v[68:71]
	v_mfma_f32_16x16x32_bf16 v[64:67], v[162:165], v[218:221], v[64:67]
	v_mfma_f32_16x16x32_bf16 v[120:123], v[148:151], v[184:187], v[120:123]
	v_mfma_f32_16x16x32_bf16 v[116:119], v[168:171], v[184:187], v[116:119]
	v_mfma_f32_16x16x32_bf16 v[100:103], v[148:151], v[192:195], v[100:103]
	v_mfma_f32_16x16x32_bf16 v[96:99], v[168:171], v[192:195], v[96:99]
	v_mfma_f32_16x16x32_bf16 v[84:87], v[148:151], v[214:217], v[84:87]
	v_mfma_f32_16x16x32_bf16 v[80:83], v[168:171], v[214:217], v[80:83]
	v_mfma_f32_16x16x32_bf16 v[68:71], v[148:151], v[222:225], v[68:71]
	v_mfma_f32_16x16x32_bf16 v[64:67], v[168:171], v[222:225], v[64:67]
	s_setprio 0
	s_barrier
	s_add_i32 s4, s9, s13
	v_lshl_add_u64 v[200:201], v[200:201], 0, s[58:59]
	s_mov_b32 m0, s4
	ds_read_b128 v[172:175], v167 offset:49152
	ds_read_b128 v[184:187], v167 offset:50176
	ds_read_b128 v[188:191], v167 offset:51200
	ds_read_b128 v[192:195], v167 offset:52224
	ds_read_b128 v[196:199], v167 offset:53248
	ds_read_b128 v[214:217], v167 offset:54272
	ds_read_b128 v[218:221], v167 offset:55296
	ds_read_b128 v[222:225], v167 offset:56320
	global_load_lds_dwordx4 v[200:201], off
	s_add_i32 m0, s4, 0x2000
	s_add_u32 s0, s0, 0x40080
	v_lshl_add_u64 v[200:201], v[226:227], 0, s[58:59]
	s_addc_u32 s1, s1, 0
	s_add_i32 s4, s33, s13
	global_load_lds_dwordx4 v[200:201], off
	v_lshl_add_u64 v[200:201], s[0:1], 0, v[176:177]
	s_mov_b32 m0, s4
	s_nop 0
	global_load_lds_dwordx4 v[200:201], off
	v_lshl_add_u64 v[200:201], s[0:1], 0, v[156:157]
	s_add_i32 m0, s4, 0x2000
	s_nop 0
	global_load_lds_dwordx4 v[200:201], off
	v_lshl_add_u64 v[200:201], v[228:229], 0, s[58:59]
	s_mov_b32 m0, s79
	s_nop 0
	global_load_lds_dwordx4 v[200:201], off
	v_lshl_add_u64 v[200:201], v[230:231], 0, s[58:59]
	s_mov_b32 m0, s80
	s_nop 0
	global_load_lds_dwordx4 v[200:201], off
	s_waitcnt vmcnt(8)
	s_waitcnt lgkmcnt(0)
	s_barrier
	s_setprio 1
	s_waitcnt lgkmcnt(0)
	v_mfma_f32_16x16x32_bf16 v[60:63], v[112:115], v[172:175], v[60:63]
	v_mfma_f32_16x16x32_bf16 v[56:59], v[136:139], v[172:175], v[56:59]
	v_mfma_f32_16x16x32_bf16 v[44:47], v[112:115], v[188:191], v[44:47]
	v_mfma_f32_16x16x32_bf16 v[40:43], v[136:139], v[188:191], v[40:43]
	v_mfma_f32_16x16x32_bf16 v[28:31], v[112:115], v[196:199], v[28:31]
	v_mfma_f32_16x16x32_bf16 v[24:27], v[136:139], v[196:199], v[24:27]
	v_mfma_f32_16x16x32_bf16 v[12:15], v[112:115], v[218:221], v[12:15]
	v_mfma_f32_16x16x32_bf16 v[8:11], v[136:139], v[218:221], v[8:11]
	v_mfma_f32_16x16x32_bf16 v[60:63], v[132:135], v[184:187], v[60:63]
	v_mfma_f32_16x16x32_bf16 v[56:59], v[140:143], v[184:187], v[56:59]
	v_mfma_f32_16x16x32_bf16 v[44:47], v[132:135], v[192:195], v[44:47]
	v_mfma_f32_16x16x32_bf16 v[40:43], v[140:143], v[192:195], v[40:43]
	v_mfma_f32_16x16x32_bf16 v[28:31], v[132:135], v[214:217], v[28:31]
	v_mfma_f32_16x16x32_bf16 v[24:27], v[140:143], v[214:217], v[24:27]
	v_mfma_f32_16x16x32_bf16 v[12:15], v[132:135], v[222:225], v[12:15]
	v_mfma_f32_16x16x32_bf16 v[8:11], v[140:143], v[222:225], v[8:11]
	s_setprio 0
	s_setprio 1
	v_mfma_f32_16x16x32_bf16 v[52:55], v[144:147], v[172:175], v[52:55]
	v_mfma_f32_16x16x32_bf16 v[48:51], v[162:165], v[172:175], v[48:51]
	v_mfma_f32_16x16x32_bf16 v[36:39], v[144:147], v[188:191], v[36:39]
	v_mfma_f32_16x16x32_bf16 v[32:35], v[162:165], v[188:191], v[32:35]
	v_mfma_f32_16x16x32_bf16 v[20:23], v[144:147], v[196:199], v[20:23]
	v_mfma_f32_16x16x32_bf16 v[16:19], v[162:165], v[196:199], v[16:19]
	v_mfma_f32_16x16x32_bf16 v[4:7], v[144:147], v[218:221], v[4:7]
	v_mfma_f32_16x16x32_bf16 v[0:3], v[162:165], v[218:221], v[0:3]
	v_mfma_f32_16x16x32_bf16 v[52:55], v[148:151], v[184:187], v[52:55]
	v_mfma_f32_16x16x32_bf16 v[48:51], v[168:171], v[184:187], v[48:51]
	v_mfma_f32_16x16x32_bf16 v[36:39], v[148:151], v[192:195], v[36:39]
	v_mfma_f32_16x16x32_bf16 v[32:35], v[168:171], v[192:195], v[32:35]
	v_mfma_f32_16x16x32_bf16 v[20:23], v[148:151], v[214:217], v[20:23]
	v_mfma_f32_16x16x32_bf16 v[16:19], v[168:171], v[214:217], v[16:19]
	v_mfma_f32_16x16x32_bf16 v[4:7], v[148:151], v[222:225], v[4:7]
	v_mfma_f32_16x16x32_bf16 v[0:3], v[168:171], v[222:225], v[0:3]
	s_setprio 0
	s_barrier
	s_add_i32 s8, s8, 2
	s_add_u32 s2, s2, 0x100
	s_addc_u32 s3, s3, 0
	s_add_u32 s6, s6, 0x100
	s_addc_u32 s7, s7, 0
	s_cmp_gt_u32 s8, 13
	s_cbranch_scc0 .LBB0_454
	s_branch .Lpeel_exit_0

.Lpeel_exit_0:
	s_and_b64 vcc, exec, s[34:35]
	s_cbranch_vccz .LBB0_457
	s_barrier

.LBB0_526:
	s_add_u32 s36, s36, 0x40080
	s_addc_u32 s37, s37, 0
	s_add_u32 s9, s4, 0x100
	s_addc_u32 s33, s5, 0
	s_mov_b32 s46, -2
	s_mov_b64 s[58:59], 0x80
	s_add_u32 s4, s36, 0xfffc0080
	s_addc_u32 s5, s37, -1
	s_add_i32 s47, 0, 0x10000
	s_cmp_eq_u32 s46, 12
	s_cselect_b32 s5, s1, s5
	s_cselect_b32 s4, s0, s4
	v_add_u32_e32 v151, s47, v149
	s_cselect_b32 s49, s3, s33
	s_cselect_b32 s48, s2, s9
	s_add_i32 s54, 0, 0x14000
	ds_read_b128 v[128:131], v151
	ds_read_b128 v[144:147], v151 offset:1024
	ds_read_b128 v[152:155], v151 offset:2048
	ds_read_b128 v[156:159], v151 offset:3072
	v_add_u32_e32 v151, s54, v149
	ds_read_b128 v[160:163], v151
	ds_read_b128 v[164:167], v151 offset:1024
	ds_read_b128 v[168:171], v151 offset:2048
	ds_read_b128 v[172:175], v151 offset:3072
	v_lshl_add_u64 v[200:201], s[36:37], 0, v[140:141]
	s_add_i32 m0, s79, 0xc000
	ds_read_b128 v[184:187], v150
	ds_read_b128 v[188:191], v150 offset:1024
	ds_read_b128 v[192:195], v150 offset:2048
	ds_read_b128 v[196:199], v150 offset:3072
	ds_read_b128 v[214:217], v150 offset:4096
	ds_read_b128 v[218:221], v150 offset:5120
	ds_read_b128 v[222:225], v150 offset:6144
	ds_read_b128 v[226:229], v150 offset:7168
	global_load_lds_dwordx4 v[200:201], off
	v_lshl_add_u64 v[200:201], s[36:37], 0, v[142:143]
	s_add_i32 m0, s79, 0xe000
	s_nop 0
	global_load_lds_dwordx4 v[200:201], off
	s_waitcnt vmcnt(8)
	s_waitcnt lgkmcnt(0)
	s_barrier
	s_setprio 1
	s_waitcnt lgkmcnt(0)
	v_mfma_f32_16x16x32_bf16 v[124:127], v[128:131], v[184:187], 0
	v_mfma_f32_16x16x32_bf16 v[120:123], v[152:155], v[184:187], 0
	v_mfma_f32_16x16x32_bf16 v[116:119], v[128:131], v[192:195], 0
	v_mfma_f32_16x16x32_bf16 v[112:115], v[152:155], v[192:195], 0
	v_mfma_f32_16x16x32_bf16 v[108:111], v[128:131], v[214:217], 0
	v_mfma_f32_16x16x32_bf16 v[104:107], v[152:155], v[214:217], 0
	v_mfma_f32_16x16x32_bf16 v[100:103], v[128:131], v[222:225], 0
	v_mfma_f32_16x16x32_bf16 v[96:99], v[152:155], v[222:225], 0
	v_mfma_f32_16x16x32_bf16 v[124:127], v[144:147], v[188:191], v[124:127]
	v_mfma_f32_16x16x32_bf16 v[120:123], v[156:159], v[188:191], v[120:123]
	v_mfma_f32_16x16x32_bf16 v[116:119], v[144:147], v[196:199], v[116:119]
	v_mfma_f32_16x16x32_bf16 v[112:115], v[156:159], v[196:199], v[112:115]
	v_mfma_f32_16x16x32_bf16 v[108:111], v[144:147], v[218:221], v[108:111]
	v_mfma_f32_16x16x32_bf16 v[104:107], v[156:159], v[218:221], v[104:107]
	v_mfma_f32_16x16x32_bf16 v[100:103], v[144:147], v[226:229], v[100:103]
	v_mfma_f32_16x16x32_bf16 v[96:99], v[156:159], v[226:229], v[96:99]
	s_setprio 0
	s_setprio 1
	v_mfma_f32_16x16x32_bf16 v[60:63], v[160:163], v[184:187], 0
	v_mfma_f32_16x16x32_bf16 v[56:59], v[168:171], v[184:187], 0
	v_mfma_f32_16x16x32_bf16 v[52:55], v[160:163], v[192:195], 0
	v_mfma_f32_16x16x32_bf16 v[48:51], v[168:171], v[192:195], 0
	v_mfma_f32_16x16x32_bf16 v[44:47], v[160:163], v[214:217], 0
	v_mfma_f32_16x16x32_bf16 v[40:43], v[168:171], v[214:217], 0
	v_mfma_f32_16x16x32_bf16 v[36:39], v[160:163], v[222:225], 0
	v_mfma_f32_16x16x32_bf16 v[32:35], v[168:171], v[222:225], 0
	v_mfma_f32_16x16x32_bf16 v[60:63], v[164:167], v[188:191], v[60:63]
	v_mfma_f32_16x16x32_bf16 v[56:59], v[172:175], v[188:191], v[56:59]
	v_mfma_f32_16x16x32_bf16 v[52:55], v[164:167], v[196:199], v[52:55]
	v_mfma_f32_16x16x32_bf16 v[48:51], v[172:175], v[196:199], v[48:51]
	v_mfma_f32_16x16x32_bf16 v[44:47], v[164:167], v[218:221], v[44:47]
	v_mfma_f32_16x16x32_bf16 v[40:43], v[172:175], v[218:221], v[40:43]
	v_mfma_f32_16x16x32_bf16 v[36:39], v[164:167], v[226:229], v[36:39]
	v_mfma_f32_16x16x32_bf16 v[32:35], v[172:175], v[226:229], v[32:35]
	s_setprio 0
	s_barrier
	s_add_i32 s47, s47, s21
	v_lshl_add_u64 v[200:201], s[48:49], 0, v[134:135]
	s_mov_b32 m0, s47
	ds_read_b128 v[184:187], v150 offset:16384
	ds_read_b128 v[188:191], v150 offset:17408
	ds_read_b128 v[192:195], v150 offset:18432
	ds_read_b128 v[196:199], v150 offset:19456
	ds_read_b128 v[214:217], v150 offset:20480
	ds_read_b128 v[218:221], v150 offset:21504
	ds_read_b128 v[222:225], v150 offset:22528
	ds_read_b128 v[226:229], v150 offset:23552
	global_load_lds_dwordx4 v[200:201], off
	s_add_i32 m0, s47, 0x2000
	v_lshl_add_u64 v[230:231], s[48:49], 0, v[138:139]
	s_add_u32 s48, s48, s40
	s_addc_u32 s49, s49, s41
	s_add_i32 s47, s54, s21
	global_load_lds_dwordx4 v[230:231], off
	v_lshl_add_u64 v[232:233], s[48:49], 0, v[134:135]
	s_mov_b32 m0, s47
	v_lshl_add_u64 v[234:235], s[48:49], 0, v[138:139]
	global_load_lds_dwordx4 v[232:233], off
	s_add_i32 m0, s47, 0x2000
	v_lshl_add_u64 v[236:237], s[4:5], 0, v[132:133]
	global_load_lds_dwordx4 v[234:235], off
	s_mov_b32 m0, s79
	v_lshl_add_u64 v[238:239], s[4:5], 0, v[136:137]
	global_load_lds_dwordx4 v[236:237], off
	s_mov_b32 m0, s80
	s_nop 0
	global_load_lds_dwordx4 v[238:239], off
	s_waitcnt vmcnt(8)
	s_waitcnt lgkmcnt(0)
	s_barrier
	s_setprio 1
	s_waitcnt lgkmcnt(0)
	v_mfma_f32_16x16x32_bf16 v[92:95], v[128:131], v[184:187], 0
	v_mfma_f32_16x16x32_bf16 v[88:91], v[152:155], v[184:187], 0
	v_mfma_f32_16x16x32_bf16 v[84:87], v[128:131], v[192:195], 0
	v_mfma_f32_16x16x32_bf16 v[80:83], v[152:155], v[192:195], 0
	v_mfma_f32_16x16x32_bf16 v[76:79], v[128:131], v[214:217], 0
	v_mfma_f32_16x16x32_bf16 v[72:75], v[152:155], v[214:217], 0
	v_mfma_f32_16x16x32_bf16 v[68:71], v[128:131], v[222:225], 0
	v_mfma_f32_16x16x32_bf16 v[64:67], v[152:155], v[222:225], 0
	v_mfma_f32_16x16x32_bf16 v[92:95], v[144:147], v[188:191], v[92:95]
	v_mfma_f32_16x16x32_bf16 v[88:91], v[156:159], v[188:191], v[88:91]
	v_mfma_f32_16x16x32_bf16 v[84:87], v[144:147], v[196:199], v[84:87]
	v_mfma_f32_16x16x32_bf16 v[80:83], v[156:159], v[196:199], v[80:83]
	v_mfma_f32_16x16x32_bf16 v[76:79], v[144:147], v[218:221], v[76:79]
	v_mfma_f32_16x16x32_bf16 v[72:75], v[156:159], v[218:221], v[72:75]
	v_mfma_f32_16x16x32_bf16 v[68:71], v[144:147], v[226:229], v[68:71]
	v_mfma_f32_16x16x32_bf16 v[64:67], v[156:159], v[226:229], v[64:67]
	s_setprio 0
	s_setprio 1
	v_mfma_f32_16x16x32_bf16 v[28:31], v[160:163], v[184:187], 0
	v_mfma_f32_16x16x32_bf16 v[24:27], v[168:171], v[184:187], 0
	v_mfma_f32_16x16x32_bf16 v[20:23], v[160:163], v[192:195], 0
	v_mfma_f32_16x16x32_bf16 v[16:19], v[168:171], v[192:195], 0
	v_mfma_f32_16x16x32_bf16 v[12:15], v[160:163], v[214:217], 0
	v_mfma_f32_16x16x32_bf16 v[8:11], v[168:171], v[214:217], 0
	v_mfma_f32_16x16x32_bf16 v[4:7], v[160:163], v[222:225], 0
	v_mfma_f32_16x16x32_bf16 v[0:3], v[168:171], v[222:225], 0
	v_mfma_f32_16x16x32_bf16 v[28:31], v[164:167], v[188:191], v[28:31]
	v_mfma_f32_16x16x32_bf16 v[24:27], v[172:175], v[188:191], v[24:27]
	v_mfma_f32_16x16x32_bf16 v[20:23], v[164:167], v[196:199], v[20:23]
	v_mfma_f32_16x16x32_bf16 v[16:19], v[172:175], v[196:199], v[16:19]
	v_mfma_f32_16x16x32_bf16 v[12:15], v[164:167], v[218:221], v[12:15]
	v_mfma_f32_16x16x32_bf16 v[8:11], v[172:175], v[218:221], v[8:11]
	v_mfma_f32_16x16x32_bf16 v[4:7], v[164:167], v[226:229], v[4:7]
	v_mfma_f32_16x16x32_bf16 v[0:3], v[172:175], v[226:229], v[0:3]
	s_setprio 0
	s_barrier
	s_add_i32 s47, 0, 0x18000
	v_add_u32_e32 v151, s47, v149
	s_add_i32 s48, 0, 0x1c000
	ds_read_b128 v[128:131], v151
	ds_read_b128 v[144:147], v151 offset:1024
	ds_read_b128 v[152:155], v151 offset:2048
	ds_read_b128 v[156:159], v151 offset:3072
	v_add_u32_e32 v151, s48, v149
	ds_read_b128 v[160:163], v151
	ds_read_b128 v[164:167], v151 offset:1024
	ds_read_b128 v[168:171], v151 offset:2048
	ds_read_b128 v[172:175], v151 offset:3072
	s_add_u32 s4, s4, 0x40000
	s_addc_u32 s5, s5, 0
	s_mov_b32 m0, s81
	v_lshl_add_u64 v[240:241], s[4:5], 0, v[132:133]
	ds_read_b128 v[184:187], v150 offset:32768
	ds_read_b128 v[188:191], v150 offset:33792
	ds_read_b128 v[192:195], v150 offset:34816
	ds_read_b128 v[196:199], v150 offset:35840
	ds_read_b128 v[214:217], v150 offset:36864
	ds_read_b128 v[218:221], v150 offset:37888
	ds_read_b128 v[222:225], v150 offset:38912
	ds_read_b128 v[226:229], v150 offset:39936
	global_load_lds_dwordx4 v[240:241], off
	v_lshl_add_u64 v[240:241], s[4:5], 0, v[136:137]
	s_mov_b32 m0, s82
	s_nop 0
	global_load_lds_dwordx4 v[240:241], off
	s_waitcnt vmcnt(8)
	s_waitcnt lgkmcnt(0)
	s_barrier
	s_setprio 1
	s_waitcnt lgkmcnt(0)
	v_mfma_f32_16x16x32_bf16 v[124:127], v[128:131], v[184:187], v[124:127]
	v_mfma_f32_16x16x32_bf16 v[120:123], v[152:155], v[184:187], v[120:123]
	v_mfma_f32_16x16x32_bf16 v[116:119], v[128:131], v[192:195], v[116:119]
	v_mfma_f32_16x16x32_bf16 v[112:115], v[152:155], v[192:195], v[112:115]
	v_mfma_f32_16x16x32_bf16 v[108:111], v[128:131], v[214:217], v[108:111]
	v_mfma_f32_16x16x32_bf16 v[104:107], v[152:155], v[214:217], v[104:107]
	v_mfma_f32_16x16x32_bf16 v[100:103], v[128:131], v[222:225], v[100:103]
	v_mfma_f32_16x16x32_bf16 v[96:99], v[152:155], v[222:225], v[96:99]
	v_mfma_f32_16x16x32_bf16 v[124:127], v[144:147], v[188:191], v[124:127]
	v_mfma_f32_16x16x32_bf16 v[120:123], v[156:159], v[188:191], v[120:123]
	v_mfma_f32_16x16x32_bf16 v[116:119], v[144:147], v[196:199], v[116:119]
	v_mfma_f32_16x16x32_bf16 v[112:115], v[156:159], v[196:199], v[112:115]
	v_mfma_f32_16x16x32_bf16 v[108:111], v[144:147], v[218:221], v[108:111]
	v_mfma_f32_16x16x32_bf16 v[104:107], v[156:159], v[218:221], v[104:107]
	v_mfma_f32_16x16x32_bf16 v[100:103], v[144:147], v[226:229], v[100:103]
	v_mfma_f32_16x16x32_bf16 v[96:99], v[156:159], v[226:229], v[96:99]
	s_setprio 0
	s_setprio 1
	v_mfma_f32_16x16x32_bf16 v[60:63], v[160:163], v[184:187], v[60:63]
	v_mfma_f32_16x16x32_bf16 v[56:59], v[168:171], v[184:187], v[56:59]
	v_mfma_f32_16x16x32_bf16 v[52:55], v[160:163], v[192:195], v[52:55]
	v_mfma_f32_16x16x32_bf16 v[48:51], v[168:171], v[192:195], v[48:51]
	v_mfma_f32_16x16x32_bf16 v[44:47], v[160:163], v[214:217], v[44:47]
	v_mfma_f32_16x16x32_bf16 v[40:43], v[168:171], v[214:217], v[40:43]
	v_mfma_f32_16x16x32_bf16 v[36:39], v[160:163], v[222:225], v[36:39]
	v_mfma_f32_16x16x32_bf16 v[32:35], v[168:171], v[222:225], v[32:35]
	v_mfma_f32_16x16x32_bf16 v[60:63], v[164:167], v[188:191], v[60:63]
	v_mfma_f32_16x16x32_bf16 v[56:59], v[172:175], v[188:191], v[56:59]
	v_mfma_f32_16x16x32_bf16 v[52:55], v[164:167], v[196:199], v[52:55]
	v_mfma_f32_16x16x32_bf16 v[48:51], v[172:175], v[196:199], v[48:51]
	v_mfma_f32_16x16x32_bf16 v[44:47], v[164:167], v[218:221], v[44:47]
	v_mfma_f32_16x16x32_bf16 v[40:43], v[172:175], v[218:221], v[40:43]
	v_mfma_f32_16x16x32_bf16 v[36:39], v[164:167], v[226:229], v[36:39]
	v_mfma_f32_16x16x32_bf16 v[32:35], v[172:175], v[226:229], v[32:35]
	s_setprio 0
	s_barrier
	s_add_i32 s4, s47, s21
	v_lshl_add_u64 v[200:201], v[200:201], 0, s[58:59]
	s_mov_b32 m0, s4
	ds_read_b128 v[184:187], v150 offset:49152
	ds_read_b128 v[188:191], v150 offset:50176
	ds_read_b128 v[192:195], v150 offset:51200
	ds_read_b128 v[196:199], v150 offset:52224
	ds_read_b128 v[214:217], v150 offset:53248
	ds_read_b128 v[218:221], v150 offset:54272
	ds_read_b128 v[222:225], v150 offset:55296
	ds_read_b128 v[226:229], v150 offset:56320
	global_load_lds_dwordx4 v[200:201], off
	v_lshl_add_u64 v[200:201], v[230:231], 0, s[58:59]
	s_add_i32 m0, s4, 0x2000
	s_add_i32 s4, s48, s21
	global_load_lds_dwordx4 v[200:201], off
	v_lshl_add_u64 v[200:201], v[232:233], 0, s[58:59]
	s_mov_b32 m0, s4
	s_nop 0
	global_load_lds_dwordx4 v[200:201], off
	v_lshl_add_u64 v[200:201], v[234:235], 0, s[58:59]
	s_add_i32 m0, s4, 0x2000
	s_nop 0
	global_load_lds_dwordx4 v[200:201], off
	v_lshl_add_u64 v[200:201], v[236:237], 0, s[58:59]
	s_mov_b32 m0, s85
	s_nop 0
	global_load_lds_dwordx4 v[200:201], off
	v_lshl_add_u64 v[200:201], v[238:239], 0, s[58:59]
	s_mov_b32 m0, s86
	s_nop 0
	global_load_lds_dwordx4 v[200:201], off
	s_waitcnt vmcnt(8)
	s_waitcnt lgkmcnt(0)
	s_barrier
	s_setprio 1
	s_waitcnt lgkmcnt(0)
	v_mfma_f32_16x16x32_bf16 v[92:95], v[128:131], v[184:187], v[92:95]
	v_mfma_f32_16x16x32_bf16 v[88:91], v[152:155], v[184:187], v[88:91]
	v_mfma_f32_16x16x32_bf16 v[84:87], v[128:131], v[192:195], v[84:87]
	v_mfma_f32_16x16x32_bf16 v[80:83], v[152:155], v[192:195], v[80:83]
	v_mfma_f32_16x16x32_bf16 v[76:79], v[128:131], v[214:217], v[76:79]
	v_mfma_f32_16x16x32_bf16 v[72:75], v[152:155], v[214:217], v[72:75]
	v_mfma_f32_16x16x32_bf16 v[68:71], v[128:131], v[222:225], v[68:71]
	v_mfma_f32_16x16x32_bf16 v[64:67], v[152:155], v[222:225], v[64:67]
	v_mfma_f32_16x16x32_bf16 v[92:95], v[144:147], v[188:191], v[92:95]
	v_mfma_f32_16x16x32_bf16 v[88:91], v[156:159], v[188:191], v[88:91]
	v_mfma_f32_16x16x32_bf16 v[84:87], v[144:147], v[196:199], v[84:87]
	v_mfma_f32_16x16x32_bf16 v[80:83], v[156:159], v[196:199], v[80:83]
	v_mfma_f32_16x16x32_bf16 v[76:79], v[144:147], v[218:221], v[76:79]
	v_mfma_f32_16x16x32_bf16 v[72:75], v[156:159], v[218:221], v[72:75]
	v_mfma_f32_16x16x32_bf16 v[68:71], v[144:147], v[226:229], v[68:71]
	v_mfma_f32_16x16x32_bf16 v[64:67], v[156:159], v[226:229], v[64:67]
	s_setprio 0
	s_setprio 1
	v_mfma_f32_16x16x32_bf16 v[28:31], v[160:163], v[184:187], v[28:31]
	v_mfma_f32_16x16x32_bf16 v[24:27], v[168:171], v[184:187], v[24:27]
	v_mfma_f32_16x16x32_bf16 v[20:23], v[160:163], v[192:195], v[20:23]
	v_mfma_f32_16x16x32_bf16 v[16:19], v[168:171], v[192:195], v[16:19]
	v_mfma_f32_16x16x32_bf16 v[12:15], v[160:163], v[214:217], v[12:15]
	v_mfma_f32_16x16x32_bf16 v[8:11], v[168:171], v[214:217], v[8:11]
	v_mfma_f32_16x16x32_bf16 v[4:7], v[160:163], v[222:225], v[4:7]
	v_mfma_f32_16x16x32_bf16 v[0:3], v[168:171], v[222:225], v[0:3]
	v_mfma_f32_16x16x32_bf16 v[28:31], v[164:167], v[188:191], v[28:31]
	v_mfma_f32_16x16x32_bf16 v[24:27], v[172:175], v[188:191], v[24:27]
	v_mfma_f32_16x16x32_bf16 v[20:23], v[164:167], v[196:199], v[20:23]
	v_mfma_f32_16x16x32_bf16 v[16:19], v[172:175], v[196:199], v[16:19]
	v_mfma_f32_16x16x32_bf16 v[12:15], v[164:167], v[218:221], v[12:15]
	v_mfma_f32_16x16x32_bf16 v[8:11], v[172:175], v[218:221], v[8:11]
	v_mfma_f32_16x16x32_bf16 v[4:7], v[164:167], v[226:229], v[4:7]
	v_mfma_f32_16x16x32_bf16 v[0:3], v[172:175], v[226:229], v[0:3]
	s_setprio 0
	s_barrier
	s_add_i32 s46, s46, 2
	s_add_u32 s36, s36, 0x100
	s_addc_u32 s37, s37, 0
	s_add_u32 s9, s9, 0x100
	s_addc_u32 s33, s33, 0
	s_cmp_gt_u32 s46, 13
	s_cbranch_scc0 .LBB0_527
	s_branch .Lpeel_exit_1

.Lpeel_exit_1:
	s_and_b64 vcc, exec, s[44:45]
	s_cbranch_vccz .LBB0_530
	s_barrier

.LBB0_581:
	s_add_u32 s50, s6, 0x80
	s_addc_u32 s51, s7, 0
	s_add_u32 s41, s48, 0x100
	v_lshl_add_u64 v[128:129], s[50:51], 0, v[152:153]
	v_lshl_add_u64 v[130:131], s[50:51], 0, v[154:155]
	s_addc_u32 s43, s49, 0
	s_mov_b32 vcc_lo, -2
	s_mov_b64 s[48:49], 0
	s_mov_b64 s[64:65], 0x80
	s_add_u32 s50, s6, s48
	s_addc_u32 s51, s7, s49
	s_add_u32 s50, s50, 0x100
	s_addc_u32 s51, s51, 0
	s_add_u32 s57, s41, s48
	s_addc_u32 s58, s43, s49
	s_add_i32 s59, 0, 0x10000
	s_cmpk_eq_i32 s48, 0x700
	s_cselect_b32 s53, s45, s51
	s_cselect_b32 s52, s44, s50
	v_add_u32_e32 v156, s59, v161
	s_cselect_b32 s51, s47, s58
	s_cselect_b32 s50, s46, s57
	s_add_i32 s57, 0, 0x14000
	ds_read_b128 v[132:135], v156
	ds_read_b128 v[136:139], v156 offset:1024
	ds_read_b128 v[140:143], v156 offset:2048
	ds_read_b128 v[164:167], v156 offset:3072
	v_add_u32_e32 v156, s57, v161
	ds_read_b128 v[168:171], v156
	ds_read_b128 v[172:175], v156 offset:1024
	ds_read_b128 v[184:187], v156 offset:2048
	ds_read_b128 v[188:191], v156 offset:3072
	v_lshl_add_u64 v[156:157], v[130:131], 0, s[48:49]
	s_add_i32 m0, s33, 0xc000
	ds_read_b128 v[192:195], v163
	ds_read_b128 v[196:199], v163 offset:1024
	ds_read_b128 v[214:217], v163 offset:2048
	ds_read_b128 v[218:221], v163 offset:3072
	ds_read_b128 v[222:225], v163 offset:4096
	ds_read_b128 v[226:229], v163 offset:5120
	ds_read_b128 v[230:233], v163 offset:6144
	ds_read_b128 v[234:237], v163 offset:7168
	global_load_lds_dwordx4 v[156:157], off
	v_lshl_add_u64 v[156:157], v[128:129], 0, s[48:49]
	s_add_i32 m0, s33, 0xe000
	s_nop 0
	global_load_lds_dwordx4 v[156:157], off
	s_waitcnt vmcnt(8)
	s_waitcnt lgkmcnt(0)
	s_barrier
	s_setprio 1
	s_waitcnt lgkmcnt(0)
	v_mfma_f32_16x16x32_bf16 v[124:127], v[132:135], v[192:195], 0
	v_mfma_f32_16x16x32_bf16 v[120:123], v[140:143], v[192:195], 0
	v_mfma_f32_16x16x32_bf16 v[108:111], v[132:135], v[214:217], 0
	v_mfma_f32_16x16x32_bf16 v[104:107], v[140:143], v[214:217], 0
	v_mfma_f32_16x16x32_bf16 v[92:95], v[132:135], v[222:225], 0
	v_mfma_f32_16x16x32_bf16 v[88:91], v[140:143], v[222:225], 0
	v_mfma_f32_16x16x32_bf16 v[76:79], v[132:135], v[230:233], 0
	v_mfma_f32_16x16x32_bf16 v[72:75], v[140:143], v[230:233], 0
	v_mfma_f32_16x16x32_bf16 v[124:127], v[136:139], v[196:199], v[124:127]
	v_mfma_f32_16x16x32_bf16 v[120:123], v[164:167], v[196:199], v[120:123]
	v_mfma_f32_16x16x32_bf16 v[108:111], v[136:139], v[218:221], v[108:111]
	v_mfma_f32_16x16x32_bf16 v[104:107], v[164:167], v[218:221], v[104:107]
	v_mfma_f32_16x16x32_bf16 v[92:95], v[136:139], v[226:229], v[92:95]
	v_mfma_f32_16x16x32_bf16 v[88:91], v[164:167], v[226:229], v[88:91]
	v_mfma_f32_16x16x32_bf16 v[76:79], v[136:139], v[234:237], v[76:79]
	v_mfma_f32_16x16x32_bf16 v[72:75], v[164:167], v[234:237], v[72:75]
	s_setprio 0
	s_setprio 1
	v_mfma_f32_16x16x32_bf16 v[116:119], v[168:171], v[192:195], 0
	v_mfma_f32_16x16x32_bf16 v[112:115], v[184:187], v[192:195], 0
	v_mfma_f32_16x16x32_bf16 v[100:103], v[168:171], v[214:217], 0
	v_mfma_f32_16x16x32_bf16 v[96:99], v[184:187], v[214:217], 0
	v_mfma_f32_16x16x32_bf16 v[84:87], v[168:171], v[222:225], 0
	v_mfma_f32_16x16x32_bf16 v[80:83], v[184:187], v[222:225], 0
	v_mfma_f32_16x16x32_bf16 v[68:71], v[168:171], v[230:233], 0
	v_mfma_f32_16x16x32_bf16 v[64:67], v[184:187], v[230:233], 0
	v_mfma_f32_16x16x32_bf16 v[116:119], v[172:175], v[196:199], v[116:119]
	v_mfma_f32_16x16x32_bf16 v[112:115], v[188:191], v[196:199], v[112:115]
	v_mfma_f32_16x16x32_bf16 v[100:103], v[172:175], v[218:221], v[100:103]
	v_mfma_f32_16x16x32_bf16 v[96:99], v[188:191], v[218:221], v[96:99]
	v_mfma_f32_16x16x32_bf16 v[84:87], v[172:175], v[226:229], v[84:87]
	v_mfma_f32_16x16x32_bf16 v[80:83], v[188:191], v[226:229], v[80:83]
	v_mfma_f32_16x16x32_bf16 v[68:71], v[172:175], v[234:237], v[68:71]
	v_mfma_f32_16x16x32_bf16 v[64:67], v[188:191], v[234:237], v[64:67]
	s_setprio 0
	s_barrier
	s_add_i32 s58, s59, s23
	v_lshl_add_u64 v[156:157], s[50:51], 0, v[146:147]
	s_mov_b32 m0, s58
	ds_read_b128 v[192:195], v163 offset:16384
	ds_read_b128 v[196:199], v163 offset:17408
	ds_read_b128 v[214:217], v163 offset:18432
	ds_read_b128 v[218:221], v163 offset:19456
	ds_read_b128 v[222:225], v163 offset:20480
	ds_read_b128 v[226:229], v163 offset:21504
	ds_read_b128 v[230:233], v163 offset:22528
	ds_read_b128 v[234:237], v163 offset:23552
	global_load_lds_dwordx4 v[156:157], off
	s_add_i32 m0, s58, 0x2000
	s_add_u32 s58, s50, 0x40000
	v_lshl_add_u64 v[200:201], s[50:51], 0, v[150:151]
	s_addc_u32 s59, s51, 0
	s_add_i32 s57, s57, s23
	global_load_lds_dwordx4 v[200:201], off
	v_lshl_add_u64 v[238:239], s[58:59], 0, v[146:147]
	s_mov_b32 m0, s57
	v_lshl_add_u64 v[240:241], s[52:53], 0, v[148:149]
	global_load_lds_dwordx4 v[238:239], off
	v_lshl_add_u64 v[238:239], s[58:59], 0, v[150:151]
	s_add_i32 m0, s57, 0x2000
	s_nop 0
	global_load_lds_dwordx4 v[238:239], off
	v_lshl_add_u64 v[238:239], s[52:53], 0, v[144:145]
	s_mov_b32 m0, s33
	s_nop 0
	global_load_lds_dwordx4 v[238:239], off
	s_mov_b32 m0, s83
	s_nop 0
	global_load_lds_dwordx4 v[240:241], off
	s_waitcnt vmcnt(8)
	s_waitcnt lgkmcnt(0)
	s_barrier
	s_setprio 1
	s_waitcnt lgkmcnt(0)
	v_mfma_f32_16x16x32_bf16 v[60:63], v[132:135], v[192:195], 0
	v_mfma_f32_16x16x32_bf16 v[56:59], v[140:143], v[192:195], 0
	v_mfma_f32_16x16x32_bf16 v[44:47], v[132:135], v[214:217], 0
	v_mfma_f32_16x16x32_bf16 v[40:43], v[140:143], v[214:217], 0
	v_mfma_f32_16x16x32_bf16 v[28:31], v[132:135], v[222:225], 0
	v_mfma_f32_16x16x32_bf16 v[24:27], v[140:143], v[222:225], 0
	v_mfma_f32_16x16x32_bf16 v[12:15], v[132:135], v[230:233], 0
	v_mfma_f32_16x16x32_bf16 v[8:11], v[140:143], v[230:233], 0
	v_mfma_f32_16x16x32_bf16 v[60:63], v[136:139], v[196:199], v[60:63]
	v_mfma_f32_16x16x32_bf16 v[56:59], v[164:167], v[196:199], v[56:59]
	v_mfma_f32_16x16x32_bf16 v[44:47], v[136:139], v[218:221], v[44:47]
	v_mfma_f32_16x16x32_bf16 v[40:43], v[164:167], v[218:221], v[40:43]
	v_mfma_f32_16x16x32_bf16 v[28:31], v[136:139], v[226:229], v[28:31]
	v_mfma_f32_16x16x32_bf16 v[24:27], v[164:167], v[226:229], v[24:27]
	v_mfma_f32_16x16x32_bf16 v[12:15], v[136:139], v[234:237], v[12:15]
	v_mfma_f32_16x16x32_bf16 v[8:11], v[164:167], v[234:237], v[8:11]
	s_setprio 0
	s_setprio 1
	v_mfma_f32_16x16x32_bf16 v[52:55], v[168:171], v[192:195], 0
	v_mfma_f32_16x16x32_bf16 v[48:51], v[184:187], v[192:195], 0
	v_mfma_f32_16x16x32_bf16 v[36:39], v[168:171], v[214:217], 0
	v_mfma_f32_16x16x32_bf16 v[32:35], v[184:187], v[214:217], 0
	v_mfma_f32_16x16x32_bf16 v[20:23], v[168:171], v[222:225], 0
	v_mfma_f32_16x16x32_bf16 v[16:19], v[184:187], v[222:225], 0
	v_mfma_f32_16x16x32_bf16 v[4:7], v[168:171], v[230:233], 0
	v_mfma_f32_16x16x32_bf16 v[0:3], v[184:187], v[230:233], 0
	v_mfma_f32_16x16x32_bf16 v[52:55], v[172:175], v[196:199], v[52:55]
	v_mfma_f32_16x16x32_bf16 v[48:51], v[188:191], v[196:199], v[48:51]
	v_mfma_f32_16x16x32_bf16 v[36:39], v[172:175], v[218:221], v[36:39]
	v_mfma_f32_16x16x32_bf16 v[32:35], v[188:191], v[218:221], v[32:35]
	v_mfma_f32_16x16x32_bf16 v[20:23], v[172:175], v[226:229], v[20:23]
	v_mfma_f32_16x16x32_bf16 v[16:19], v[188:191], v[226:229], v[16:19]
	v_mfma_f32_16x16x32_bf16 v[4:7], v[172:175], v[234:237], v[4:7]
	v_mfma_f32_16x16x32_bf16 v[0:3], v[188:191], v[234:237], v[0:3]
	s_setprio 0
	s_barrier
	s_add_i32 s57, 0, 0x18000
	v_add_u32_e32 v158, s57, v161
	s_add_i32 s58, 0, 0x1c000
	ds_read_b128 v[132:135], v158
	ds_read_b128 v[136:139], v158 offset:1024
	ds_read_b128 v[140:143], v158 offset:2048
	ds_read_b128 v[164:167], v158 offset:3072
	v_add_u32_e32 v158, s58, v161
	ds_read_b128 v[168:171], v158
	ds_read_b128 v[172:175], v158 offset:1024
	ds_read_b128 v[184:187], v158 offset:2048
	ds_read_b128 v[188:191], v158 offset:3072
	s_add_u32 s52, s52, s0
	s_addc_u32 s53, s53, s1
	s_mov_b32 m0, s84
	v_lshl_add_u64 v[242:243], s[52:53], 0, v[144:145]
	ds_read_b128 v[192:195], v163 offset:32768
	ds_read_b128 v[196:199], v163 offset:33792
	ds_read_b128 v[214:217], v163 offset:34816
	ds_read_b128 v[218:221], v163 offset:35840
	ds_read_b128 v[222:225], v163 offset:36864
	ds_read_b128 v[226:229], v163 offset:37888
	ds_read_b128 v[230:233], v163 offset:38912
	ds_read_b128 v[234:237], v163 offset:39936
	global_load_lds_dwordx4 v[242:243], off
	v_lshl_add_u64 v[242:243], s[52:53], 0, v[148:149]
	s_mov_b32 m0, s85
	s_nop 0
	global_load_lds_dwordx4 v[242:243], off
	s_waitcnt vmcnt(8)
	s_waitcnt lgkmcnt(0)
	s_barrier
	s_setprio 1
	s_waitcnt lgkmcnt(0)
	v_mfma_f32_16x16x32_bf16 v[124:127], v[132:135], v[192:195], v[124:127]
	v_mfma_f32_16x16x32_bf16 v[120:123], v[140:143], v[192:195], v[120:123]
	v_mfma_f32_16x16x32_bf16 v[108:111], v[132:135], v[214:217], v[108:111]
	v_mfma_f32_16x16x32_bf16 v[104:107], v[140:143], v[214:217], v[104:107]
	v_mfma_f32_16x16x32_bf16 v[92:95], v[132:135], v[222:225], v[92:95]
	v_mfma_f32_16x16x32_bf16 v[88:91], v[140:143], v[222:225], v[88:91]
	v_mfma_f32_16x16x32_bf16 v[76:79], v[132:135], v[230:233], v[76:79]
	v_mfma_f32_16x16x32_bf16 v[72:75], v[140:143], v[230:233], v[72:75]
	v_mfma_f32_16x16x32_bf16 v[124:127], v[136:139], v[196:199], v[124:127]
	v_mfma_f32_16x16x32_bf16 v[120:123], v[164:167], v[196:199], v[120:123]
	v_mfma_f32_16x16x32_bf16 v[108:111], v[136:139], v[218:221], v[108:111]
	v_mfma_f32_16x16x32_bf16 v[104:107], v[164:167], v[218:221], v[104:107]
	v_mfma_f32_16x16x32_bf16 v[92:95], v[136:139], v[226:229], v[92:95]
	v_mfma_f32_16x16x32_bf16 v[88:91], v[164:167], v[226:229], v[88:91]
	v_mfma_f32_16x16x32_bf16 v[76:79], v[136:139], v[234:237], v[76:79]
	v_mfma_f32_16x16x32_bf16 v[72:75], v[164:167], v[234:237], v[72:75]
	s_setprio 0
	s_setprio 1
	v_mfma_f32_16x16x32_bf16 v[116:119], v[168:171], v[192:195], v[116:119]
	v_mfma_f32_16x16x32_bf16 v[112:115], v[184:187], v[192:195], v[112:115]
	v_mfma_f32_16x16x32_bf16 v[100:103], v[168:171], v[214:217], v[100:103]
	v_mfma_f32_16x16x32_bf16 v[96:99], v[184:187], v[214:217], v[96:99]
	v_mfma_f32_16x16x32_bf16 v[84:87], v[168:171], v[222:225], v[84:87]
	v_mfma_f32_16x16x32_bf16 v[80:83], v[184:187], v[222:225], v[80:83]
	v_mfma_f32_16x16x32_bf16 v[68:71], v[168:171], v[230:233], v[68:71]
	v_mfma_f32_16x16x32_bf16 v[64:67], v[184:187], v[230:233], v[64:67]
	v_mfma_f32_16x16x32_bf16 v[116:119], v[172:175], v[196:199], v[116:119]
	v_mfma_f32_16x16x32_bf16 v[112:115], v[188:191], v[196:199], v[112:115]
	v_mfma_f32_16x16x32_bf16 v[100:103], v[172:175], v[218:221], v[100:103]
	v_mfma_f32_16x16x32_bf16 v[96:99], v[188:191], v[218:221], v[96:99]
	v_mfma_f32_16x16x32_bf16 v[84:87], v[172:175], v[226:229], v[84:87]
	v_mfma_f32_16x16x32_bf16 v[80:83], v[188:191], v[226:229], v[80:83]
	v_mfma_f32_16x16x32_bf16 v[68:71], v[172:175], v[234:237], v[68:71]
	v_mfma_f32_16x16x32_bf16 v[64:67], v[188:191], v[234:237], v[64:67]
	s_setprio 0
	s_barrier
	s_add_i32 s52, s57, s23
	v_lshl_add_u64 v[156:157], v[156:157], 0, s[64:65]
	s_mov_b32 m0, s52
	ds_read_b128 v[192:195], v163 offset:49152
	ds_read_b128 v[196:199], v163 offset:50176
	ds_read_b128 v[214:217], v163 offset:51200
	ds_read_b128 v[218:221], v163 offset:52224
	ds_read_b128 v[222:225], v163 offset:53248
	ds_read_b128 v[226:229], v163 offset:54272
	ds_read_b128 v[230:233], v163 offset:55296
	ds_read_b128 v[234:237], v163 offset:56320
	global_load_lds_dwordx4 v[156:157], off
	s_add_i32 m0, s52, 0x2000
	s_add_u32 s50, s50, 0x40080
	v_lshl_add_u64 v[156:157], v[200:201], 0, s[64:65]
	s_addc_u32 s51, s51, 0
	s_add_i32 s52, s58, s23
	global_load_lds_dwordx4 v[156:157], off
	v_lshl_add_u64 v[156:157], s[50:51], 0, v[146:147]
	s_mov_b32 m0, s52
	s_nop 0
	global_load_lds_dwordx4 v[156:157], off
	v_lshl_add_u64 v[156:157], s[50:51], 0, v[150:151]
	s_add_i32 m0, s52, 0x2000
	s_nop 0
	global_load_lds_dwordx4 v[156:157], off
	v_lshl_add_u64 v[156:157], v[238:239], 0, s[64:65]
	s_mov_b32 m0, s88
	s_nop 0
	global_load_lds_dwordx4 v[156:157], off
	v_lshl_add_u64 v[156:157], v[240:241], 0, s[64:65]
	s_mov_b32 m0, s89
	s_nop 0
	global_load_lds_dwordx4 v[156:157], off
	s_waitcnt vmcnt(8)
	s_waitcnt lgkmcnt(0)
	s_barrier
	s_setprio 1
	s_waitcnt lgkmcnt(0)
	v_mfma_f32_16x16x32_bf16 v[60:63], v[132:135], v[192:195], v[60:63]
	v_mfma_f32_16x16x32_bf16 v[56:59], v[140:143], v[192:195], v[56:59]
	v_mfma_f32_16x16x32_bf16 v[44:47], v[132:135], v[214:217], v[44:47]
	v_mfma_f32_16x16x32_bf16 v[40:43], v[140:143], v[214:217], v[40:43]
	v_mfma_f32_16x16x32_bf16 v[28:31], v[132:135], v[222:225], v[28:31]
	v_mfma_f32_16x16x32_bf16 v[24:27], v[140:143], v[222:225], v[24:27]
	v_mfma_f32_16x16x32_bf16 v[12:15], v[132:135], v[230:233], v[12:15]
	v_mfma_f32_16x16x32_bf16 v[8:11], v[140:143], v[230:233], v[8:11]
	v_mfma_f32_16x16x32_bf16 v[60:63], v[136:139], v[196:199], v[60:63]
	v_mfma_f32_16x16x32_bf16 v[56:59], v[164:167], v[196:199], v[56:59]
	v_mfma_f32_16x16x32_bf16 v[44:47], v[136:139], v[218:221], v[44:47]
	v_mfma_f32_16x16x32_bf16 v[40:43], v[164:167], v[218:221], v[40:43]
	v_mfma_f32_16x16x32_bf16 v[28:31], v[136:139], v[226:229], v[28:31]
	v_mfma_f32_16x16x32_bf16 v[24:27], v[164:167], v[226:229], v[24:27]
	v_mfma_f32_16x16x32_bf16 v[12:15], v[136:139], v[234:237], v[12:15]
	v_mfma_f32_16x16x32_bf16 v[8:11], v[164:167], v[234:237], v[8:11]
	s_setprio 0
	s_setprio 1
	v_mfma_f32_16x16x32_bf16 v[52:55], v[168:171], v[192:195], v[52:55]
	v_mfma_f32_16x16x32_bf16 v[48:51], v[184:187], v[192:195], v[48:51]
	v_mfma_f32_16x16x32_bf16 v[36:39], v[168:171], v[214:217], v[36:39]
	v_mfma_f32_16x16x32_bf16 v[32:35], v[184:187], v[214:217], v[32:35]
	v_mfma_f32_16x16x32_bf16 v[20:23], v[168:171], v[222:225], v[20:23]
	v_mfma_f32_16x16x32_bf16 v[16:19], v[184:187], v[222:225], v[16:19]
	v_mfma_f32_16x16x32_bf16 v[4:7], v[168:171], v[230:233], v[4:7]
	v_mfma_f32_16x16x32_bf16 v[0:3], v[184:187], v[230:233], v[0:3]
	v_mfma_f32_16x16x32_bf16 v[52:55], v[172:175], v[196:199], v[52:55]
	v_mfma_f32_16x16x32_bf16 v[48:51], v[188:191], v[196:199], v[48:51]
	v_mfma_f32_16x16x32_bf16 v[36:39], v[172:175], v[218:221], v[36:39]
	v_mfma_f32_16x16x32_bf16 v[32:35], v[188:191], v[218:221], v[32:35]
	v_mfma_f32_16x16x32_bf16 v[20:23], v[172:175], v[226:229], v[20:23]
	v_mfma_f32_16x16x32_bf16 v[16:19], v[188:191], v[226:229], v[16:19]
	v_mfma_f32_16x16x32_bf16 v[4:7], v[172:175], v[234:237], v[4:7]
	v_mfma_f32_16x16x32_bf16 v[0:3], v[188:191], v[234:237], v[0:3]
	s_setprio 0
	s_barrier
	s_add_i32 vcc_lo, vcc_lo, 2
	s_add_u32 s48, s48, 0x100
	s_addc_u32 s49, s49, 0
	s_cmp_gt_u32 vcc_lo, 13
	s_cbranch_scc0 .LBB0_582
	s_branch .Lpeel_exit_2

.Lpeel_exit_2:
	s_and_b64 vcc, exec, s[36:37]
	s_cbranch_vccz .LBB0_585
	s_barrier

.LBB0_634:
	s_add_u32 s2, s2, 0x40080
	s_addc_u32 s3, s3, 0
	s_add_u32 s1, s6, 0x100
	s_addc_u32 s8, s7, 0
	s_mov_b32 s9, -2
	s_mov_b64 s[58:59], 0x80
	s_add_u32 s4, s2, 0xfffc0080
	s_addc_u32 s5, s3, -1
	s_add_i32 s33, 0, 0x10000
	s_cmp_eq_u32 s9, 12
	s_cselect_b32 s7, s49, s5
	s_cselect_b32 s6, s48, s4
	s_cselect_b32 s5, s51, s8
	s_cselect_b32 s4, s50, s1
	s_add_i32 s54, 0, 0x14000
	v_add_u32_e32 v76, s33, v194
	v_add_u32_e32 v156, s54, v194
	ds_read_b128 v[32:35], v76
	ds_read_b128 v[36:39], v76 offset:1024
	ds_read_b128 v[72:75], v76 offset:2048
	ds_read_b128 v[76:79], v76 offset:3072
	ds_read_b128 v[112:115], v156
	ds_read_b128 v[116:119], v156 offset:1024
	ds_read_b128 v[152:155], v156 offset:2048
	ds_read_b128 v[156:159], v156 offset:3072
	v_lshl_add_u64 v[192:193], s[2:3], 0, v[168:169]
	s_add_i32 m0, s21, 0xc000
	ds_read_b128 v[172:175], v195
	ds_read_b128 v[184:187], v195 offset:1024
	ds_read_b128 v[188:191], v195 offset:2048
	ds_read_b128 v[196:199], v195 offset:3072
	ds_read_b128 v[214:217], v195 offset:4096
	ds_read_b128 v[218:221], v195 offset:5120
	ds_read_b128 v[222:225], v195 offset:6144
	ds_read_b128 v[226:229], v195 offset:7168
	global_load_lds_dwordx4 v[192:193], off
	v_lshl_add_u64 v[192:193], s[2:3], 0, v[170:171]
	s_add_i32 m0, s21, 0xe000
	s_nop 0
	global_load_lds_dwordx4 v[192:193], off
	s_waitcnt vmcnt(8)
	s_waitcnt lgkmcnt(0)
	s_barrier
	s_setprio 1
	s_waitcnt lgkmcnt(0)
	v_mfma_f32_16x16x32_bf16 v[148:151], v[32:35], v[172:175], 0
	v_mfma_f32_16x16x32_bf16 v[144:147], v[72:75], v[172:175], 0
	v_mfma_f32_16x16x32_bf16 v[132:135], v[32:35], v[188:191], 0
	v_mfma_f32_16x16x32_bf16 v[128:131], v[72:75], v[188:191], 0
	v_mfma_f32_16x16x32_bf16 v[108:111], v[32:35], v[214:217], 0
	v_mfma_f32_16x16x32_bf16 v[104:107], v[72:75], v[214:217], 0
	v_mfma_f32_16x16x32_bf16 v[92:95], v[32:35], v[222:225], 0
	v_mfma_f32_16x16x32_bf16 v[88:91], v[72:75], v[222:225], 0
	v_mfma_f32_16x16x32_bf16 v[148:151], v[36:39], v[184:187], v[148:151]
	v_mfma_f32_16x16x32_bf16 v[144:147], v[76:79], v[184:187], v[144:147]
	v_mfma_f32_16x16x32_bf16 v[132:135], v[36:39], v[196:199], v[132:135]
	v_mfma_f32_16x16x32_bf16 v[128:131], v[76:79], v[196:199], v[128:131]
	v_mfma_f32_16x16x32_bf16 v[108:111], v[36:39], v[218:221], v[108:111]
	v_mfma_f32_16x16x32_bf16 v[104:107], v[76:79], v[218:221], v[104:107]
	v_mfma_f32_16x16x32_bf16 v[92:95], v[36:39], v[226:229], v[92:95]
	v_mfma_f32_16x16x32_bf16 v[88:91], v[76:79], v[226:229], v[88:91]
	s_setprio 0
	s_setprio 1
	v_mfma_f32_16x16x32_bf16 v[140:143], v[112:115], v[172:175], 0
	v_mfma_f32_16x16x32_bf16 v[136:139], v[152:155], v[172:175], 0
	v_mfma_f32_16x16x32_bf16 v[124:127], v[112:115], v[188:191], 0
	v_mfma_f32_16x16x32_bf16 v[120:123], v[152:155], v[188:191], 0
	v_mfma_f32_16x16x32_bf16 v[100:103], v[112:115], v[214:217], 0
	v_mfma_f32_16x16x32_bf16 v[96:99], v[152:155], v[214:217], 0
	v_mfma_f32_16x16x32_bf16 v[84:87], v[112:115], v[222:225], 0
	v_mfma_f32_16x16x32_bf16 v[80:83], v[152:155], v[222:225], 0
	v_mfma_f32_16x16x32_bf16 v[140:143], v[116:119], v[184:187], v[140:143]
	v_mfma_f32_16x16x32_bf16 v[136:139], v[156:159], v[184:187], v[136:139]
	v_mfma_f32_16x16x32_bf16 v[124:127], v[116:119], v[196:199], v[124:127]
	v_mfma_f32_16x16x32_bf16 v[120:123], v[156:159], v[196:199], v[120:123]
	v_mfma_f32_16x16x32_bf16 v[100:103], v[116:119], v[218:221], v[100:103]
	v_mfma_f32_16x16x32_bf16 v[96:99], v[156:159], v[218:221], v[96:99]
	v_mfma_f32_16x16x32_bf16 v[84:87], v[116:119], v[226:229], v[84:87]
	v_mfma_f32_16x16x32_bf16 v[80:83], v[156:159], v[226:229], v[80:83]
	s_setprio 0
	s_barrier
	s_add_i32 s33, s33, s13
	v_lshl_add_u64 v[192:193], s[4:5], 0, v[162:163]
	s_mov_b32 m0, s33
	ds_read_b128 v[172:175], v195 offset:16384
	ds_read_b128 v[184:187], v195 offset:17408
	ds_read_b128 v[188:191], v195 offset:18432
	ds_read_b128 v[196:199], v195 offset:19456
	ds_read_b128 v[214:217], v195 offset:20480
	ds_read_b128 v[218:221], v195 offset:21504
	ds_read_b128 v[222:225], v195 offset:22528
	ds_read_b128 v[226:229], v195 offset:23552
	global_load_lds_dwordx4 v[192:193], off
	s_add_i32 m0, s33, 0x2000
	s_add_u32 s36, s4, 0x40000
	v_lshl_add_u64 v[200:201], s[4:5], 0, v[166:167]
	s_addc_u32 s37, s5, 0
	s_add_i32 s33, s54, s13
	global_load_lds_dwordx4 v[200:201], off
	v_lshl_add_u64 v[230:231], s[36:37], 0, v[162:163]
	s_mov_b32 m0, s33
	v_lshl_add_u64 v[232:233], s[6:7], 0, v[164:165]
	global_load_lds_dwordx4 v[230:231], off
	v_lshl_add_u64 v[230:231], s[36:37], 0, v[166:167]
	s_add_i32 m0, s33, 0x2000
	s_nop 0
	global_load_lds_dwordx4 v[230:231], off
	v_lshl_add_u64 v[230:231], s[6:7], 0, v[160:161]
	s_mov_b32 m0, s21
	s_nop 0
	global_load_lds_dwordx4 v[230:231], off
	s_mov_b32 m0, s23
	s_nop 0
	global_load_lds_dwordx4 v[232:233], off
	s_waitcnt vmcnt(8)
	s_waitcnt lgkmcnt(0)
	s_barrier
	s_setprio 1
	s_waitcnt lgkmcnt(0)
	v_mfma_f32_16x16x32_bf16 v[68:71], v[32:35], v[172:175], 0
	v_mfma_f32_16x16x32_bf16 v[64:67], v[72:75], v[172:175], 0
	v_mfma_f32_16x16x32_bf16 v[52:55], v[32:35], v[188:191], 0
	v_mfma_f32_16x16x32_bf16 v[48:51], v[72:75], v[188:191], 0
	v_mfma_f32_16x16x32_bf16 v[28:31], v[32:35], v[214:217], 0
	v_mfma_f32_16x16x32_bf16 v[24:27], v[72:75], v[214:217], 0
	v_mfma_f32_16x16x32_bf16 v[12:15], v[32:35], v[222:225], 0
	v_mfma_f32_16x16x32_bf16 v[8:11], v[72:75], v[222:225], 0
	v_mfma_f32_16x16x32_bf16 v[68:71], v[36:39], v[184:187], v[68:71]
	v_mfma_f32_16x16x32_bf16 v[64:67], v[76:79], v[184:187], v[64:67]
	v_mfma_f32_16x16x32_bf16 v[52:55], v[36:39], v[196:199], v[52:55]
	v_mfma_f32_16x16x32_bf16 v[48:51], v[76:79], v[196:199], v[48:51]
	v_mfma_f32_16x16x32_bf16 v[28:31], v[36:39], v[218:221], v[28:31]
	v_mfma_f32_16x16x32_bf16 v[24:27], v[76:79], v[218:221], v[24:27]
	v_mfma_f32_16x16x32_bf16 v[12:15], v[36:39], v[226:229], v[12:15]
	v_mfma_f32_16x16x32_bf16 v[8:11], v[76:79], v[226:229], v[8:11]
	s_setprio 0
	s_setprio 1
	v_mfma_f32_16x16x32_bf16 v[44:47], v[112:115], v[188:191], 0
	v_mfma_f32_16x16x32_bf16 v[40:43], v[152:155], v[188:191], 0
	v_mfma_f32_16x16x32_bf16 v[20:23], v[112:115], v[214:217], 0
	v_mfma_f32_16x16x32_bf16 v[16:19], v[152:155], v[214:217], 0
	v_mfma_f32_16x16x32_bf16 v[4:7], v[112:115], v[222:225], 0
	v_mfma_f32_16x16x32_bf16 v[0:3], v[152:155], v[222:225], 0
	v_mfma_f32_16x16x32_bf16 v[32:35], v[112:115], v[172:175], 0
	v_mfma_f32_16x16x32_bf16 v[36:39], v[152:155], v[172:175], 0
	v_mfma_f32_16x16x32_bf16 v[44:47], v[116:119], v[196:199], v[44:47]
	v_mfma_f32_16x16x32_bf16 v[40:43], v[156:159], v[196:199], v[40:43]
	v_mfma_f32_16x16x32_bf16 v[20:23], v[116:119], v[218:221], v[20:23]
	v_mfma_f32_16x16x32_bf16 v[16:19], v[156:159], v[218:221], v[16:19]
	v_mfma_f32_16x16x32_bf16 v[4:7], v[116:119], v[226:229], v[4:7]
	v_mfma_f32_16x16x32_bf16 v[0:3], v[156:159], v[226:229], v[0:3]
	v_mfma_f32_16x16x32_bf16 v[32:35], v[116:119], v[184:187], v[32:35]
	v_mfma_f32_16x16x32_bf16 v[36:39], v[156:159], v[184:187], v[36:39]
	s_setprio 0
	s_barrier
	s_add_i32 s33, 0, 0x18000
	s_add_i32 s36, 0, 0x1c000
	v_add_u32_e32 v76, s33, v194
	v_add_u32_e32 v156, s36, v194
	ds_read_b128 v[56:59], v76
	ds_read_b128 v[60:63], v76 offset:1024
	ds_read_b128 v[72:75], v76 offset:2048
	ds_read_b128 v[76:79], v76 offset:3072
	ds_read_b128 v[112:115], v156
	ds_read_b128 v[116:119], v156 offset:1024
	ds_read_b128 v[152:155], v156 offset:2048
	ds_read_b128 v[156:159], v156 offset:3072
	s_add_u32 s6, s6, 0x40000
	s_addc_u32 s7, s7, 0
	s_mov_b32 m0, s52
	v_lshl_add_u64 v[234:235], s[6:7], 0, v[160:161]
	ds_read_b128 v[172:175], v195 offset:32768
	ds_read_b128 v[184:187], v195 offset:33792
	ds_read_b128 v[188:191], v195 offset:34816
	ds_read_b128 v[196:199], v195 offset:35840
	ds_read_b128 v[214:217], v195 offset:36864
	ds_read_b128 v[218:221], v195 offset:37888
	ds_read_b128 v[222:225], v195 offset:38912
	ds_read_b128 v[226:229], v195 offset:39936
	global_load_lds_dwordx4 v[234:235], off
	v_lshl_add_u64 v[234:235], s[6:7], 0, v[164:165]
	s_mov_b32 m0, s53
	s_nop 0
	global_load_lds_dwordx4 v[234:235], off
	s_waitcnt vmcnt(8)
	s_waitcnt lgkmcnt(0)
	s_barrier
	s_setprio 1
	s_waitcnt lgkmcnt(0)
	v_mfma_f32_16x16x32_bf16 v[148:151], v[56:59], v[172:175], v[148:151]
	v_mfma_f32_16x16x32_bf16 v[144:147], v[72:75], v[172:175], v[144:147]
	v_mfma_f32_16x16x32_bf16 v[132:135], v[56:59], v[188:191], v[132:135]
	v_mfma_f32_16x16x32_bf16 v[128:131], v[72:75], v[188:191], v[128:131]
	v_mfma_f32_16x16x32_bf16 v[108:111], v[56:59], v[214:217], v[108:111]
	v_mfma_f32_16x16x32_bf16 v[104:107], v[72:75], v[214:217], v[104:107]
	v_mfma_f32_16x16x32_bf16 v[92:95], v[56:59], v[222:225], v[92:95]
	v_mfma_f32_16x16x32_bf16 v[88:91], v[72:75], v[222:225], v[88:91]
	v_mfma_f32_16x16x32_bf16 v[148:151], v[60:63], v[184:187], v[148:151]
	v_mfma_f32_16x16x32_bf16 v[144:147], v[76:79], v[184:187], v[144:147]
	v_mfma_f32_16x16x32_bf16 v[132:135], v[60:63], v[196:199], v[132:135]
	v_mfma_f32_16x16x32_bf16 v[128:131], v[76:79], v[196:199], v[128:131]
	v_mfma_f32_16x16x32_bf16 v[108:111], v[60:63], v[218:221], v[108:111]
	v_mfma_f32_16x16x32_bf16 v[104:107], v[76:79], v[218:221], v[104:107]
	v_mfma_f32_16x16x32_bf16 v[92:95], v[60:63], v[226:229], v[92:95]
	v_mfma_f32_16x16x32_bf16 v[88:91], v[76:79], v[226:229], v[88:91]
	s_setprio 0
	s_setprio 1
	v_mfma_f32_16x16x32_bf16 v[140:143], v[112:115], v[172:175], v[140:143]
	v_mfma_f32_16x16x32_bf16 v[136:139], v[152:155], v[172:175], v[136:139]
	v_mfma_f32_16x16x32_bf16 v[124:127], v[112:115], v[188:191], v[124:127]
	v_mfma_f32_16x16x32_bf16 v[120:123], v[152:155], v[188:191], v[120:123]
	v_mfma_f32_16x16x32_bf16 v[100:103], v[112:115], v[214:217], v[100:103]
	v_mfma_f32_16x16x32_bf16 v[96:99], v[152:155], v[214:217], v[96:99]
	v_mfma_f32_16x16x32_bf16 v[84:87], v[112:115], v[222:225], v[84:87]
	v_mfma_f32_16x16x32_bf16 v[80:83], v[152:155], v[222:225], v[80:83]
	v_mfma_f32_16x16x32_bf16 v[140:143], v[116:119], v[184:187], v[140:143]
	v_mfma_f32_16x16x32_bf16 v[136:139], v[156:159], v[184:187], v[136:139]
	v_mfma_f32_16x16x32_bf16 v[124:127], v[116:119], v[196:199], v[124:127]
	v_mfma_f32_16x16x32_bf16 v[120:123], v[156:159], v[196:199], v[120:123]
	v_mfma_f32_16x16x32_bf16 v[100:103], v[116:119], v[218:221], v[100:103]
	v_mfma_f32_16x16x32_bf16 v[96:99], v[156:159], v[218:221], v[96:99]
	v_mfma_f32_16x16x32_bf16 v[84:87], v[116:119], v[226:229], v[84:87]
	v_mfma_f32_16x16x32_bf16 v[80:83], v[156:159], v[226:229], v[80:83]
	s_setprio 0
	s_barrier
	s_add_i32 s6, s33, s13
	v_lshl_add_u64 v[192:193], v[192:193], 0, s[58:59]
	s_mov_b32 m0, s6
	ds_read_b128 v[172:175], v195 offset:49152
	ds_read_b128 v[184:187], v195 offset:50176
	ds_read_b128 v[188:191], v195 offset:51200
	ds_read_b128 v[196:199], v195 offset:52224
	ds_read_b128 v[214:217], v195 offset:53248
	ds_read_b128 v[218:221], v195 offset:54272
	ds_read_b128 v[222:225], v195 offset:55296
	ds_read_b128 v[226:229], v195 offset:56320
	global_load_lds_dwordx4 v[192:193], off
	s_add_i32 m0, s6, 0x2000
	s_add_u32 s4, s4, 0x40080
	v_lshl_add_u64 v[192:193], v[200:201], 0, s[58:59]
	s_addc_u32 s5, s5, 0
	s_add_i32 s6, s36, s13
	global_load_lds_dwordx4 v[192:193], off
	v_lshl_add_u64 v[192:193], s[4:5], 0, v[162:163]
	s_mov_b32 m0, s6
	s_nop 0
	global_load_lds_dwordx4 v[192:193], off
	v_lshl_add_u64 v[192:193], s[4:5], 0, v[166:167]
	s_add_i32 m0, s6, 0x2000
	s_nop 0
	global_load_lds_dwordx4 v[192:193], off
	v_lshl_add_u64 v[192:193], v[230:231], 0, s[58:59]
	s_mov_b32 m0, s78
	s_nop 0
	global_load_lds_dwordx4 v[192:193], off
	v_lshl_add_u64 v[192:193], v[232:233], 0, s[58:59]
	s_mov_b32 m0, s79
	s_nop 0
	global_load_lds_dwordx4 v[192:193], off
	s_waitcnt vmcnt(8)
	s_waitcnt lgkmcnt(0)
	s_barrier
	s_setprio 1
	s_waitcnt lgkmcnt(0)
	v_mfma_f32_16x16x32_bf16 v[68:71], v[56:59], v[172:175], v[68:71]
	v_mfma_f32_16x16x32_bf16 v[64:67], v[72:75], v[172:175], v[64:67]
	v_mfma_f32_16x16x32_bf16 v[52:55], v[56:59], v[188:191], v[52:55]
	v_mfma_f32_16x16x32_bf16 v[48:51], v[72:75], v[188:191], v[48:51]
	v_mfma_f32_16x16x32_bf16 v[28:31], v[56:59], v[214:217], v[28:31]
	v_mfma_f32_16x16x32_bf16 v[24:27], v[72:75], v[214:217], v[24:27]
	v_mfma_f32_16x16x32_bf16 v[12:15], v[56:59], v[222:225], v[12:15]
	v_mfma_f32_16x16x32_bf16 v[8:11], v[72:75], v[222:225], v[8:11]
	v_mfma_f32_16x16x32_bf16 v[68:71], v[60:63], v[184:187], v[68:71]
	v_mfma_f32_16x16x32_bf16 v[64:67], v[76:79], v[184:187], v[64:67]
	v_mfma_f32_16x16x32_bf16 v[52:55], v[60:63], v[196:199], v[52:55]
	v_mfma_f32_16x16x32_bf16 v[48:51], v[76:79], v[196:199], v[48:51]
	v_mfma_f32_16x16x32_bf16 v[28:31], v[60:63], v[218:221], v[28:31]
	v_mfma_f32_16x16x32_bf16 v[24:27], v[76:79], v[218:221], v[24:27]
	v_mfma_f32_16x16x32_bf16 v[12:15], v[60:63], v[226:229], v[12:15]
	v_mfma_f32_16x16x32_bf16 v[8:11], v[76:79], v[226:229], v[8:11]
	s_setprio 0
	s_setprio 1
	v_mfma_f32_16x16x32_bf16 v[32:35], v[112:115], v[172:175], v[32:35]
	v_mfma_f32_16x16x32_bf16 v[60:63], v[116:119], v[184:187], v[32:35]
	v_mfma_f32_16x16x32_bf16 v[32:35], v[152:155], v[172:175], v[36:39]
	v_mfma_f32_16x16x32_bf16 v[56:59], v[156:159], v[184:187], v[32:35]
	v_mfma_f32_16x16x32_bf16 v[32:35], v[112:115], v[188:191], v[44:47]
	v_mfma_f32_16x16x32_bf16 v[44:47], v[116:119], v[196:199], v[32:35]
	v_mfma_f32_16x16x32_bf16 v[32:35], v[152:155], v[188:191], v[40:43]
	v_mfma_f32_16x16x32_bf16 v[20:23], v[112:115], v[214:217], v[20:23]
	v_mfma_f32_16x16x32_bf16 v[16:19], v[152:155], v[214:217], v[16:19]
	v_mfma_f32_16x16x32_bf16 v[4:7], v[112:115], v[222:225], v[4:7]
	v_mfma_f32_16x16x32_bf16 v[0:3], v[152:155], v[222:225], v[0:3]
	v_mfma_f32_16x16x32_bf16 v[40:43], v[156:159], v[196:199], v[32:35]
	v_mfma_f32_16x16x32_bf16 v[20:23], v[116:119], v[218:221], v[20:23]
	v_mfma_f32_16x16x32_bf16 v[16:19], v[156:159], v[218:221], v[16:19]
	v_mfma_f32_16x16x32_bf16 v[4:7], v[116:119], v[226:229], v[4:7]
	v_mfma_f32_16x16x32_bf16 v[0:3], v[156:159], v[226:229], v[0:3]
	s_setprio 0
	s_barrier
	s_add_i32 s9, s9, 2
	s_add_u32 s2, s2, 0x100
	s_addc_u32 s3, s3, 0
	s_add_u32 s1, s1, 0x100
	s_addc_u32 s8, s8, 0
	s_cmp_gt_u32 s9, 13
	s_cbranch_scc0 .LBB0_635
	s_branch .Lpeel_exit_3

.Lpeel_exit_3:
	s_mov_b64 s[58:59], 0x80
	s_and_b64 vcc, exec, s[34:35]
	s_cbranch_vccz .LBB0_638
	s_barrier

.LBB0_1009:
	s_add_u32 s36, s36, 0x80
	s_addc_u32 s37, s37, 0
	s_add_u32 s8, s6, 0x100
	s_addc_u32 s9, s7, 0
	s_mov_b32 s6, 0
	s_mov_b64 s[58:59], s[10:11]
	s_mov_b64 s[64:65], 0x80
	s_add_i32 s31, s6, 2
	s_add_u32 s35, s36, 0x80
	s_addc_u32 s7, s37, 0
	s_add_i32 s52, 0, 0x10000
	s_cmp_eq_u32 s33, s6
	s_cselect_b32 s7, s1, s7
	s_cselect_b32 s6, s0, s35
	s_cselect_b32 s51, s3, s9
	s_cselect_b32 s50, s2, s8
	s_add_i32 s35, 0, 0x14000
	v_add_u32_e32 v140, s52, v213
	v_add_u32_e32 v156, s35, v213
	ds_read_b128 v[128:131], v140
	ds_read_b128 v[132:135], v140 offset:1024
	ds_read_b128 v[136:139], v140 offset:2048
	ds_read_b128 v[140:143], v140 offset:3072
	ds_read_b128 v[144:147], v156
	ds_read_b128 v[148:151], v156 offset:1024
	ds_read_b128 v[152:155], v156 offset:2048
	ds_read_b128 v[156:159], v156 offset:3072
	v_lshl_add_u64 v[200:201], s[36:37], 0, v[192:193]
	s_add_i32 m0, s23, 0xc000
	ds_read_b128 v[160:163], v214
	ds_read_b128 v[164:167], v214 offset:1024
	ds_read_b128 v[168:171], v214 offset:2048
	ds_read_b128 v[172:175], v214 offset:3072
	ds_read_b128 v[196:199], v214 offset:4096
	ds_read_b128 v[216:219], v214 offset:5120
	ds_read_b128 v[220:223], v214 offset:6144
	ds_read_b128 v[224:227], v214 offset:7168
	global_load_lds_dwordx4 v[200:201], off
	v_lshl_add_u64 v[200:201], s[36:37], 0, v[194:195]
	s_add_i32 m0, s23, 0xe000
	s_nop 0
	global_load_lds_dwordx4 v[200:201], off
	s_waitcnt vmcnt(8)
	s_waitcnt lgkmcnt(0)
	s_barrier
	s_setprio 1
	s_waitcnt lgkmcnt(0)
	v_mfma_f32_16x16x32_bf16 v[124:127], v[128:131], v[160:163], 0
	v_mfma_f32_16x16x32_bf16 v[120:123], v[136:139], v[160:163], 0
	v_mfma_f32_16x16x32_bf16 v[108:111], v[128:131], v[168:171], 0
	v_mfma_f32_16x16x32_bf16 v[104:107], v[136:139], v[168:171], 0
	v_mfma_f32_16x16x32_bf16 v[92:95], v[128:131], v[196:199], 0
	v_mfma_f32_16x16x32_bf16 v[88:91], v[136:139], v[196:199], 0
	v_mfma_f32_16x16x32_bf16 v[76:79], v[128:131], v[220:223], 0
	v_mfma_f32_16x16x32_bf16 v[72:75], v[136:139], v[220:223], 0
	v_mfma_f32_16x16x32_bf16 v[124:127], v[132:135], v[164:167], v[124:127]
	v_mfma_f32_16x16x32_bf16 v[120:123], v[140:143], v[164:167], v[120:123]
	v_mfma_f32_16x16x32_bf16 v[108:111], v[132:135], v[172:175], v[108:111]
	v_mfma_f32_16x16x32_bf16 v[104:107], v[140:143], v[172:175], v[104:107]
	v_mfma_f32_16x16x32_bf16 v[92:95], v[132:135], v[216:219], v[92:95]
	v_mfma_f32_16x16x32_bf16 v[88:91], v[140:143], v[216:219], v[88:91]
	v_mfma_f32_16x16x32_bf16 v[76:79], v[132:135], v[224:227], v[76:79]
	v_mfma_f32_16x16x32_bf16 v[72:75], v[140:143], v[224:227], v[72:75]
	s_setprio 0
	s_setprio 1
	v_mfma_f32_16x16x32_bf16 v[116:119], v[144:147], v[160:163], 0
	v_mfma_f32_16x16x32_bf16 v[112:115], v[152:155], v[160:163], 0
	v_mfma_f32_16x16x32_bf16 v[100:103], v[144:147], v[168:171], 0
	v_mfma_f32_16x16x32_bf16 v[96:99], v[152:155], v[168:171], 0
	v_mfma_f32_16x16x32_bf16 v[84:87], v[144:147], v[196:199], 0
	v_mfma_f32_16x16x32_bf16 v[80:83], v[152:155], v[196:199], 0
	v_mfma_f32_16x16x32_bf16 v[68:71], v[144:147], v[220:223], 0
	v_mfma_f32_16x16x32_bf16 v[64:67], v[152:155], v[220:223], 0
	v_mfma_f32_16x16x32_bf16 v[116:119], v[148:151], v[164:167], v[116:119]
	v_mfma_f32_16x16x32_bf16 v[112:115], v[156:159], v[164:167], v[112:115]
	v_mfma_f32_16x16x32_bf16 v[100:103], v[148:151], v[172:175], v[100:103]
	v_mfma_f32_16x16x32_bf16 v[96:99], v[156:159], v[172:175], v[96:99]
	v_mfma_f32_16x16x32_bf16 v[84:87], v[148:151], v[216:219], v[84:87]
	v_mfma_f32_16x16x32_bf16 v[80:83], v[156:159], v[216:219], v[80:83]
	v_mfma_f32_16x16x32_bf16 v[68:71], v[148:151], v[224:227], v[68:71]
	v_mfma_f32_16x16x32_bf16 v[64:67], v[156:159], v[224:227], v[64:67]
	s_setprio 0
	s_barrier
	s_add_i32 s52, s52, s21
	v_lshl_add_u64 v[200:201], s[50:51], 0, v[186:187]
	s_mov_b32 m0, s52
	ds_read_b128 v[160:163], v214 offset:16384
	ds_read_b128 v[164:167], v214 offset:17408
	ds_read_b128 v[168:171], v214 offset:18432
	ds_read_b128 v[172:175], v214 offset:19456
	ds_read_b128 v[196:199], v214 offset:20480
	ds_read_b128 v[216:219], v214 offset:21504
	ds_read_b128 v[220:223], v214 offset:22528
	ds_read_b128 v[224:227], v214 offset:23552
	global_load_lds_dwordx4 v[200:201], off
	s_add_i32 m0, s52, 0x2000
	v_lshl_add_u64 v[228:229], s[50:51], 0, v[190:191]
	s_add_u32 s50, s50, s58
	s_addc_u32 s51, s51, 0
	s_add_i32 s35, s35, s21
	global_load_lds_dwordx4 v[228:229], off
	v_lshl_add_u64 v[230:231], s[50:51], 0, v[186:187]
	s_mov_b32 m0, s35
	v_lshl_add_u64 v[232:233], s[50:51], 0, v[190:191]
	global_load_lds_dwordx4 v[230:231], off
	s_add_i32 m0, s35, 0x2000
	v_lshl_add_u64 v[234:235], s[6:7], 0, v[184:185]
	global_load_lds_dwordx4 v[232:233], off
	s_mov_b32 m0, s23
	v_lshl_add_u64 v[236:237], s[6:7], 0, v[188:189]
	global_load_lds_dwordx4 v[234:235], off
	s_mov_b32 m0, s55
	s_nop 0
	global_load_lds_dwordx4 v[236:237], off
	s_waitcnt vmcnt(8)
	s_waitcnt lgkmcnt(0)
	s_barrier
	s_setprio 1
	s_waitcnt lgkmcnt(0)
	v_mfma_f32_16x16x32_bf16 v[60:63], v[128:131], v[160:163], 0
	v_mfma_f32_16x16x32_bf16 v[56:59], v[136:139], v[160:163], 0
	v_mfma_f32_16x16x32_bf16 v[44:47], v[128:131], v[168:171], 0
	v_mfma_f32_16x16x32_bf16 v[40:43], v[136:139], v[168:171], 0
	v_mfma_f32_16x16x32_bf16 v[28:31], v[128:131], v[196:199], 0
	v_mfma_f32_16x16x32_bf16 v[24:27], v[136:139], v[196:199], 0
	v_mfma_f32_16x16x32_bf16 v[12:15], v[128:131], v[220:223], 0
	v_mfma_f32_16x16x32_bf16 v[8:11], v[136:139], v[220:223], 0
	v_mfma_f32_16x16x32_bf16 v[60:63], v[132:135], v[164:167], v[60:63]
	v_mfma_f32_16x16x32_bf16 v[56:59], v[140:143], v[164:167], v[56:59]
	v_mfma_f32_16x16x32_bf16 v[44:47], v[132:135], v[172:175], v[44:47]
	v_mfma_f32_16x16x32_bf16 v[40:43], v[140:143], v[172:175], v[40:43]
	v_mfma_f32_16x16x32_bf16 v[28:31], v[132:135], v[216:219], v[28:31]
	v_mfma_f32_16x16x32_bf16 v[24:27], v[140:143], v[216:219], v[24:27]
	v_mfma_f32_16x16x32_bf16 v[12:15], v[132:135], v[224:227], v[12:15]
	v_mfma_f32_16x16x32_bf16 v[8:11], v[140:143], v[224:227], v[8:11]
	s_setprio 0
	s_setprio 1
	v_mfma_f32_16x16x32_bf16 v[52:55], v[144:147], v[160:163], 0
	v_mfma_f32_16x16x32_bf16 v[48:51], v[152:155], v[160:163], 0
	v_mfma_f32_16x16x32_bf16 v[36:39], v[144:147], v[168:171], 0
	v_mfma_f32_16x16x32_bf16 v[32:35], v[152:155], v[168:171], 0
	v_mfma_f32_16x16x32_bf16 v[20:23], v[144:147], v[196:199], 0
	v_mfma_f32_16x16x32_bf16 v[16:19], v[152:155], v[196:199], 0
	v_mfma_f32_16x16x32_bf16 v[4:7], v[144:147], v[220:223], 0
	v_mfma_f32_16x16x32_bf16 v[0:3], v[152:155], v[220:223], 0
	v_mfma_f32_16x16x32_bf16 v[52:55], v[148:151], v[164:167], v[52:55]
	v_mfma_f32_16x16x32_bf16 v[48:51], v[156:159], v[164:167], v[48:51]
	v_mfma_f32_16x16x32_bf16 v[36:39], v[148:151], v[172:175], v[36:39]
	v_mfma_f32_16x16x32_bf16 v[32:35], v[156:159], v[172:175], v[32:35]
	v_mfma_f32_16x16x32_bf16 v[20:23], v[148:151], v[216:219], v[20:23]
	v_mfma_f32_16x16x32_bf16 v[16:19], v[156:159], v[216:219], v[16:19]
	v_mfma_f32_16x16x32_bf16 v[4:7], v[148:151], v[224:227], v[4:7]
	v_mfma_f32_16x16x32_bf16 v[0:3], v[156:159], v[224:227], v[0:3]
	s_setprio 0
	s_barrier
	s_add_i32 s35, 0, 0x18000
	s_add_i32 s50, 0, 0x1c000
	v_add_u32_e32 v140, s35, v213
	v_add_u32_e32 v156, s50, v213
	ds_read_b128 v[128:131], v140
	ds_read_b128 v[132:135], v140 offset:1024
	ds_read_b128 v[136:139], v140 offset:2048
	ds_read_b128 v[140:143], v140 offset:3072
	ds_read_b128 v[144:147], v156
	ds_read_b128 v[148:151], v156 offset:1024
	ds_read_b128 v[152:155], v156 offset:2048
	ds_read_b128 v[156:159], v156 offset:3072
	s_add_u32 s6, s6, s58
	s_addc_u32 s7, s7, 0
	s_mov_b32 m0, s78
	v_lshl_add_u64 v[238:239], s[6:7], 0, v[184:185]
	ds_read_b128 v[160:163], v214 offset:32768
	ds_read_b128 v[164:167], v214 offset:33792
	ds_read_b128 v[168:171], v214 offset:34816
	ds_read_b128 v[172:175], v214 offset:35840
	ds_read_b128 v[196:199], v214 offset:36864
	ds_read_b128 v[216:219], v214 offset:37888
	ds_read_b128 v[220:223], v214 offset:38912
	ds_read_b128 v[224:227], v214 offset:39936
	global_load_lds_dwordx4 v[238:239], off
	v_lshl_add_u64 v[238:239], s[6:7], 0, v[188:189]
	s_mov_b32 m0, s79
	s_nop 0
	global_load_lds_dwordx4 v[238:239], off
	s_waitcnt vmcnt(8)
	s_waitcnt lgkmcnt(0)
	s_barrier
	s_setprio 1
	s_waitcnt lgkmcnt(0)
	v_mfma_f32_16x16x32_bf16 v[124:127], v[128:131], v[160:163], v[124:127]
	v_mfma_f32_16x16x32_bf16 v[120:123], v[136:139], v[160:163], v[120:123]
	v_mfma_f32_16x16x32_bf16 v[108:111], v[128:131], v[168:171], v[108:111]
	v_mfma_f32_16x16x32_bf16 v[104:107], v[136:139], v[168:171], v[104:107]
	v_mfma_f32_16x16x32_bf16 v[92:95], v[128:131], v[196:199], v[92:95]
	v_mfma_f32_16x16x32_bf16 v[88:91], v[136:139], v[196:199], v[88:91]
	v_mfma_f32_16x16x32_bf16 v[76:79], v[128:131], v[220:223], v[76:79]
	v_mfma_f32_16x16x32_bf16 v[72:75], v[136:139], v[220:223], v[72:75]
	v_mfma_f32_16x16x32_bf16 v[124:127], v[132:135], v[164:167], v[124:127]
	v_mfma_f32_16x16x32_bf16 v[120:123], v[140:143], v[164:167], v[120:123]
	v_mfma_f32_16x16x32_bf16 v[108:111], v[132:135], v[172:175], v[108:111]
	v_mfma_f32_16x16x32_bf16 v[104:107], v[140:143], v[172:175], v[104:107]
	v_mfma_f32_16x16x32_bf16 v[92:95], v[132:135], v[216:219], v[92:95]
	v_mfma_f32_16x16x32_bf16 v[88:91], v[140:143], v[216:219], v[88:91]
	v_mfma_f32_16x16x32_bf16 v[76:79], v[132:135], v[224:227], v[76:79]
	v_mfma_f32_16x16x32_bf16 v[72:75], v[140:143], v[224:227], v[72:75]
	s_setprio 0
	s_setprio 1
	v_mfma_f32_16x16x32_bf16 v[116:119], v[144:147], v[160:163], v[116:119]
	v_mfma_f32_16x16x32_bf16 v[112:115], v[152:155], v[160:163], v[112:115]
	v_mfma_f32_16x16x32_bf16 v[100:103], v[144:147], v[168:171], v[100:103]
	v_mfma_f32_16x16x32_bf16 v[96:99], v[152:155], v[168:171], v[96:99]
	v_mfma_f32_16x16x32_bf16 v[84:87], v[144:147], v[196:199], v[84:87]
	v_mfma_f32_16x16x32_bf16 v[80:83], v[152:155], v[196:199], v[80:83]
	v_mfma_f32_16x16x32_bf16 v[68:71], v[144:147], v[220:223], v[68:71]
	v_mfma_f32_16x16x32_bf16 v[64:67], v[152:155], v[220:223], v[64:67]
	v_mfma_f32_16x16x32_bf16 v[116:119], v[148:151], v[164:167], v[116:119]
	v_mfma_f32_16x16x32_bf16 v[112:115], v[156:159], v[164:167], v[112:115]
	v_mfma_f32_16x16x32_bf16 v[100:103], v[148:151], v[172:175], v[100:103]
	v_mfma_f32_16x16x32_bf16 v[96:99], v[156:159], v[172:175], v[96:99]
	v_mfma_f32_16x16x32_bf16 v[84:87], v[148:151], v[216:219], v[84:87]
	v_mfma_f32_16x16x32_bf16 v[80:83], v[156:159], v[216:219], v[80:83]
	v_mfma_f32_16x16x32_bf16 v[68:71], v[148:151], v[224:227], v[68:71]
	v_mfma_f32_16x16x32_bf16 v[64:67], v[156:159], v[224:227], v[64:67]
	s_setprio 0
	s_barrier
	s_add_i32 s6, s35, s21
	v_lshl_add_u64 v[200:201], v[200:201], 0, s[64:65]
	s_mov_b32 m0, s6
	ds_read_b128 v[160:163], v214 offset:49152
	ds_read_b128 v[164:167], v214 offset:50176
	ds_read_b128 v[168:171], v214 offset:51200
	ds_read_b128 v[172:175], v214 offset:52224
	ds_read_b128 v[196:199], v214 offset:53248
	ds_read_b128 v[216:219], v214 offset:54272
	ds_read_b128 v[220:223], v214 offset:55296
	ds_read_b128 v[224:227], v214 offset:56320
	global_load_lds_dwordx4 v[200:201], off
	v_lshl_add_u64 v[200:201], v[228:229], 0, s[64:65]
	s_add_i32 m0, s6, 0x2000
	s_add_i32 s6, s50, s21
	global_load_lds_dwordx4 v[200:201], off
	v_lshl_add_u64 v[200:201], v[230:231], 0, s[64:65]
	s_mov_b32 m0, s6
	s_nop 0
	global_load_lds_dwordx4 v[200:201], off
	v_lshl_add_u64 v[200:201], v[232:233], 0, s[64:65]
	s_add_i32 m0, s6, 0x2000
	s_nop 0
	global_load_lds_dwordx4 v[200:201], off
	v_lshl_add_u64 v[200:201], v[234:235], 0, s[64:65]
	s_mov_b32 m0, s81
	s_nop 0
	global_load_lds_dwordx4 v[200:201], off
	v_lshl_add_u64 v[200:201], v[236:237], 0, s[64:65]
	s_mov_b32 m0, s82
	s_nop 0
	global_load_lds_dwordx4 v[200:201], off
	s_waitcnt vmcnt(8)
	s_waitcnt lgkmcnt(0)
	s_barrier
	s_setprio 1
	s_waitcnt lgkmcnt(0)
	v_mfma_f32_16x16x32_bf16 v[60:63], v[128:131], v[160:163], v[60:63]
	v_mfma_f32_16x16x32_bf16 v[56:59], v[136:139], v[160:163], v[56:59]
	v_mfma_f32_16x16x32_bf16 v[44:47], v[128:131], v[168:171], v[44:47]
	v_mfma_f32_16x16x32_bf16 v[40:43], v[136:139], v[168:171], v[40:43]
	v_mfma_f32_16x16x32_bf16 v[28:31], v[128:131], v[196:199], v[28:31]
	v_mfma_f32_16x16x32_bf16 v[24:27], v[136:139], v[196:199], v[24:27]
	v_mfma_f32_16x16x32_bf16 v[12:15], v[128:131], v[220:223], v[12:15]
	v_mfma_f32_16x16x32_bf16 v[8:11], v[136:139], v[220:223], v[8:11]
	v_mfma_f32_16x16x32_bf16 v[60:63], v[132:135], v[164:167], v[60:63]
	v_mfma_f32_16x16x32_bf16 v[56:59], v[140:143], v[164:167], v[56:59]
	v_mfma_f32_16x16x32_bf16 v[44:47], v[132:135], v[172:175], v[44:47]
	v_mfma_f32_16x16x32_bf16 v[40:43], v[140:143], v[172:175], v[40:43]
	v_mfma_f32_16x16x32_bf16 v[28:31], v[132:135], v[216:219], v[28:31]
	v_mfma_f32_16x16x32_bf16 v[24:27], v[140:143], v[216:219], v[24:27]
	v_mfma_f32_16x16x32_bf16 v[12:15], v[132:135], v[224:227], v[12:15]
	v_mfma_f32_16x16x32_bf16 v[8:11], v[140:143], v[224:227], v[8:11]
	s_setprio 0
	s_setprio 1
	v_mfma_f32_16x16x32_bf16 v[52:55], v[144:147], v[160:163], v[52:55]
	v_mfma_f32_16x16x32_bf16 v[48:51], v[152:155], v[160:163], v[48:51]
	v_mfma_f32_16x16x32_bf16 v[36:39], v[144:147], v[168:171], v[36:39]
	v_mfma_f32_16x16x32_bf16 v[32:35], v[152:155], v[168:171], v[32:35]
	v_mfma_f32_16x16x32_bf16 v[20:23], v[144:147], v[196:199], v[20:23]
	v_mfma_f32_16x16x32_bf16 v[16:19], v[152:155], v[196:199], v[16:19]
	v_mfma_f32_16x16x32_bf16 v[4:7], v[144:147], v[220:223], v[4:7]
	v_mfma_f32_16x16x32_bf16 v[0:3], v[152:155], v[220:223], v[0:3]
	v_mfma_f32_16x16x32_bf16 v[52:55], v[148:151], v[164:167], v[52:55]
	v_mfma_f32_16x16x32_bf16 v[48:51], v[156:159], v[164:167], v[48:51]
	v_mfma_f32_16x16x32_bf16 v[36:39], v[148:151], v[172:175], v[36:39]
	v_mfma_f32_16x16x32_bf16 v[32:35], v[156:159], v[172:175], v[32:35]
	v_mfma_f32_16x16x32_bf16 v[20:23], v[148:151], v[216:219], v[20:23]
	v_mfma_f32_16x16x32_bf16 v[16:19], v[156:159], v[216:219], v[16:19]
	v_mfma_f32_16x16x32_bf16 v[4:7], v[148:151], v[224:227], v[4:7]
	v_mfma_f32_16x16x32_bf16 v[0:3], v[156:159], v[224:227], v[0:3]
	s_setprio 0
	s_barrier
	s_add_u32 s36, s36, 0x100
	s_addc_u32 s37, s37, 0
	s_add_u32 s8, s8, 0x100
	s_addc_u32 s9, s9, 0
	s_cmp_ge_u32 s31, s80
	s_mov_b32 s6, s31
	s_cbranch_scc0 .LBB0_1010
	s_branch .Lpeel_exit_4

.Lpeel_exit_4:
	s_and_b64 vcc, exec, s[40:41]
	s_cbranch_vccz .LBB0_1013
	s_barrier

.LBB0_1083:
	s_add_u32 s0, s0, 0x40080
	s_addc_u32 s1, s1, 0
	s_add_u32 s9, s2, 0x100
	s_addc_u32 s36, s3, 0
	s_mov_b32 s37, -2
	s_mov_b64 s[64:65], 0x80
	s_add_u32 s2, s0, 0xfffc0080
	s_addc_u32 s3, s1, -1
	s_add_i32 s54, 0, 0x10000
	s_cmp_eq_u32 s37, 12
	s_cselect_b32 s5, s47, s3
	s_cselect_b32 s4, s46, s2
	s_cselect_b32 s3, s49, s36
	s_cselect_b32 s2, s48, s9
	s_add_i32 s58, 0, 0x14000
	v_add_u32_e32 v140, s54, v173
	v_add_u32_e32 v168, s58, v173
	ds_read_b128 v[128:131], v140
	ds_read_b128 v[132:135], v140 offset:1024
	ds_read_b128 v[136:139], v140 offset:2048
	ds_read_b128 v[140:143], v140 offset:3072
	ds_read_b128 v[156:159], v168
	ds_read_b128 v[160:163], v168 offset:1024
	ds_read_b128 v[164:167], v168 offset:2048
	ds_read_b128 v[184:187], v168 offset:3072
	v_lshl_add_u64 v[170:171], s[0:1], 0, v[152:153]
	s_add_i32 m0, s79, 0xc000
	ds_read_b128 v[188:191], v175
	ds_read_b128 v[192:195], v175 offset:1024
	ds_read_b128 v[196:199], v175 offset:2048
	ds_read_b128 v[214:217], v175 offset:3072
	ds_read_b128 v[218:221], v175 offset:4096
	ds_read_b128 v[222:225], v175 offset:5120
	ds_read_b128 v[226:229], v175 offset:6144
	ds_read_b128 v[230:233], v175 offset:7168
	global_load_lds_dwordx4 v[170:171], off
	v_lshl_add_u64 v[170:171], s[0:1], 0, v[154:155]
	s_add_i32 m0, s79, 0xe000
	s_nop 0
	global_load_lds_dwordx4 v[170:171], off
	s_waitcnt vmcnt(8)
	s_waitcnt lgkmcnt(0)
	s_barrier
	s_setprio 1
	s_waitcnt lgkmcnt(0)
	v_mfma_f32_16x16x32_bf16 v[124:127], v[128:131], v[188:191], 0
	v_mfma_f32_16x16x32_bf16 v[116:119], v[136:139], v[188:191], 0
	v_mfma_f32_16x16x32_bf16 v[108:111], v[128:131], v[196:199], 0
	v_mfma_f32_16x16x32_bf16 v[100:103], v[136:139], v[196:199], 0
	v_mfma_f32_16x16x32_bf16 v[92:95], v[128:131], v[218:221], 0
	v_mfma_f32_16x16x32_bf16 v[84:87], v[136:139], v[218:221], 0
	v_mfma_f32_16x16x32_bf16 v[76:79], v[128:131], v[226:229], 0
	v_mfma_f32_16x16x32_bf16 v[68:71], v[136:139], v[226:229], 0
	v_mfma_f32_16x16x32_bf16 v[124:127], v[132:135], v[192:195], v[124:127]
	v_mfma_f32_16x16x32_bf16 v[116:119], v[140:143], v[192:195], v[116:119]
	v_mfma_f32_16x16x32_bf16 v[108:111], v[132:135], v[214:217], v[108:111]
	v_mfma_f32_16x16x32_bf16 v[100:103], v[140:143], v[214:217], v[100:103]
	v_mfma_f32_16x16x32_bf16 v[92:95], v[132:135], v[222:225], v[92:95]
	v_mfma_f32_16x16x32_bf16 v[84:87], v[140:143], v[222:225], v[84:87]
	v_mfma_f32_16x16x32_bf16 v[76:79], v[132:135], v[230:233], v[76:79]
	v_mfma_f32_16x16x32_bf16 v[68:71], v[140:143], v[230:233], v[68:71]
	s_setprio 0
	s_setprio 1
	v_mfma_f32_16x16x32_bf16 v[120:123], v[156:159], v[188:191], 0
	v_mfma_f32_16x16x32_bf16 v[112:115], v[164:167], v[188:191], 0
	v_mfma_f32_16x16x32_bf16 v[104:107], v[156:159], v[196:199], 0
	v_mfma_f32_16x16x32_bf16 v[96:99], v[164:167], v[196:199], 0
	v_mfma_f32_16x16x32_bf16 v[88:91], v[156:159], v[218:221], 0
	v_mfma_f32_16x16x32_bf16 v[80:83], v[164:167], v[218:221], 0
	v_mfma_f32_16x16x32_bf16 v[72:75], v[156:159], v[226:229], 0
	v_mfma_f32_16x16x32_bf16 v[64:67], v[164:167], v[226:229], 0
	v_mfma_f32_16x16x32_bf16 v[120:123], v[160:163], v[192:195], v[120:123]
	v_mfma_f32_16x16x32_bf16 v[112:115], v[184:187], v[192:195], v[112:115]
	v_mfma_f32_16x16x32_bf16 v[104:107], v[160:163], v[214:217], v[104:107]
	v_mfma_f32_16x16x32_bf16 v[96:99], v[184:187], v[214:217], v[96:99]
	v_mfma_f32_16x16x32_bf16 v[88:91], v[160:163], v[222:225], v[88:91]
	v_mfma_f32_16x16x32_bf16 v[80:83], v[184:187], v[222:225], v[80:83]
	v_mfma_f32_16x16x32_bf16 v[72:75], v[160:163], v[230:233], v[72:75]
	v_mfma_f32_16x16x32_bf16 v[64:67], v[184:187], v[230:233], v[64:67]
	s_setprio 0
	s_barrier
	s_add_i32 s54, s54, s78
	v_lshl_add_u64 v[170:171], s[2:3], 0, v[146:147]
	s_mov_b32 m0, s54
	ds_read_b128 v[188:191], v175 offset:16384
	ds_read_b128 v[192:195], v175 offset:17408
	ds_read_b128 v[196:199], v175 offset:18432
	ds_read_b128 v[214:217], v175 offset:19456
	ds_read_b128 v[218:221], v175 offset:20480
	ds_read_b128 v[222:225], v175 offset:21504
	ds_read_b128 v[226:229], v175 offset:22528
	ds_read_b128 v[230:233], v175 offset:23552
	global_load_lds_dwordx4 v[170:171], off
	s_add_i32 m0, s54, 0x2000
	s_add_u32 s92, s2, 0x40000
	v_lshl_add_u64 v[200:201], s[2:3], 0, v[150:151]
	s_addc_u32 s93, s3, 0
	s_add_i32 s54, s58, s78
	global_load_lds_dwordx4 v[200:201], off
	v_lshl_add_u64 v[234:235], s[92:93], 0, v[146:147]
	s_mov_b32 m0, s54
	v_lshl_add_u64 v[236:237], s[4:5], 0, v[148:149]
	global_load_lds_dwordx4 v[234:235], off
	v_lshl_add_u64 v[234:235], s[92:93], 0, v[150:151]
	s_add_i32 m0, s54, 0x2000
	s_nop 0
	global_load_lds_dwordx4 v[234:235], off
	v_lshl_add_u64 v[234:235], s[4:5], 0, v[144:145]
	s_mov_b32 m0, s79
	s_nop 0
	global_load_lds_dwordx4 v[234:235], off
	s_mov_b32 m0, s80
	s_nop 0
	global_load_lds_dwordx4 v[236:237], off
	s_waitcnt vmcnt(8)
	s_waitcnt lgkmcnt(0)
	s_barrier
	s_setprio 1
	s_waitcnt lgkmcnt(0)
	v_mfma_f32_16x16x32_bf16 v[60:63], v[128:131], v[188:191], 0
	v_mfma_f32_16x16x32_bf16 v[52:55], v[136:139], v[188:191], 0
	v_mfma_f32_16x16x32_bf16 v[44:47], v[128:131], v[196:199], 0
	v_mfma_f32_16x16x32_bf16 v[36:39], v[136:139], v[196:199], 0
	v_mfma_f32_16x16x32_bf16 v[28:31], v[128:131], v[218:221], 0
	v_mfma_f32_16x16x32_bf16 v[20:23], v[136:139], v[218:221], 0
	v_mfma_f32_16x16x32_bf16 v[12:15], v[128:131], v[226:229], 0
	v_mfma_f32_16x16x32_bf16 v[4:7], v[136:139], v[226:229], 0
	v_mfma_f32_16x16x32_bf16 v[60:63], v[132:135], v[192:195], v[60:63]
	v_mfma_f32_16x16x32_bf16 v[52:55], v[140:143], v[192:195], v[52:55]
	v_mfma_f32_16x16x32_bf16 v[44:47], v[132:135], v[214:217], v[44:47]
	v_mfma_f32_16x16x32_bf16 v[36:39], v[140:143], v[214:217], v[36:39]
	v_mfma_f32_16x16x32_bf16 v[28:31], v[132:135], v[222:225], v[28:31]
	v_mfma_f32_16x16x32_bf16 v[20:23], v[140:143], v[222:225], v[20:23]
	v_mfma_f32_16x16x32_bf16 v[12:15], v[132:135], v[230:233], v[12:15]
	v_mfma_f32_16x16x32_bf16 v[4:7], v[140:143], v[230:233], v[4:7]
	s_setprio 0
	s_setprio 1
	v_mfma_f32_16x16x32_bf16 v[56:59], v[156:159], v[188:191], 0
	v_mfma_f32_16x16x32_bf16 v[48:51], v[164:167], v[188:191], 0
	v_mfma_f32_16x16x32_bf16 v[40:43], v[156:159], v[196:199], 0
	v_mfma_f32_16x16x32_bf16 v[32:35], v[164:167], v[196:199], 0
	v_mfma_f32_16x16x32_bf16 v[24:27], v[156:159], v[218:221], 0
	v_mfma_f32_16x16x32_bf16 v[16:19], v[164:167], v[218:221], 0
	v_mfma_f32_16x16x32_bf16 v[8:11], v[156:159], v[226:229], 0
	v_mfma_f32_16x16x32_bf16 v[0:3], v[164:167], v[226:229], 0
	v_mfma_f32_16x16x32_bf16 v[56:59], v[160:163], v[192:195], v[56:59]
	v_mfma_f32_16x16x32_bf16 v[48:51], v[184:187], v[192:195], v[48:51]
	v_mfma_f32_16x16x32_bf16 v[40:43], v[160:163], v[214:217], v[40:43]
	v_mfma_f32_16x16x32_bf16 v[32:35], v[184:187], v[214:217], v[32:35]
	v_mfma_f32_16x16x32_bf16 v[24:27], v[160:163], v[222:225], v[24:27]
	v_mfma_f32_16x16x32_bf16 v[16:19], v[184:187], v[222:225], v[16:19]
	v_mfma_f32_16x16x32_bf16 v[8:11], v[160:163], v[230:233], v[8:11]
	v_mfma_f32_16x16x32_bf16 v[0:3], v[184:187], v[230:233], v[0:3]
	s_setprio 0
	s_barrier
	s_add_i32 s54, 0, 0x18000
	s_add_i32 s58, 0, 0x1c000
	v_add_u32_e32 v140, s54, v173
	v_add_u32_e32 v168, s58, v173
	ds_read_b128 v[128:131], v140
	ds_read_b128 v[132:135], v140 offset:1024
	ds_read_b128 v[136:139], v140 offset:2048
	ds_read_b128 v[140:143], v140 offset:3072
	ds_read_b128 v[156:159], v168
	ds_read_b128 v[160:163], v168 offset:1024
	ds_read_b128 v[164:167], v168 offset:2048
	ds_read_b128 v[184:187], v168 offset:3072
	s_add_u32 s4, s4, 0x40000
	s_addc_u32 s5, s5, 0
	s_mov_b32 m0, s81
	v_lshl_add_u64 v[238:239], s[4:5], 0, v[144:145]
	ds_read_b128 v[188:191], v175 offset:32768
	ds_read_b128 v[192:195], v175 offset:33792
	ds_read_b128 v[196:199], v175 offset:34816
	ds_read_b128 v[214:217], v175 offset:35840
	ds_read_b128 v[218:221], v175 offset:36864
	ds_read_b128 v[222:225], v175 offset:37888
	ds_read_b128 v[226:229], v175 offset:38912
	ds_read_b128 v[230:233], v175 offset:39936
	global_load_lds_dwordx4 v[238:239], off
	v_lshl_add_u64 v[238:239], s[4:5], 0, v[148:149]
	s_mov_b32 m0, s82
	s_nop 0
	global_load_lds_dwordx4 v[238:239], off
	s_waitcnt vmcnt(8)
	s_waitcnt lgkmcnt(0)
	s_barrier
	s_setprio 1
	s_waitcnt lgkmcnt(0)
	v_mfma_f32_16x16x32_bf16 v[124:127], v[128:131], v[188:191], v[124:127]
	v_mfma_f32_16x16x32_bf16 v[116:119], v[136:139], v[188:191], v[116:119]
	v_mfma_f32_16x16x32_bf16 v[108:111], v[128:131], v[196:199], v[108:111]
	v_mfma_f32_16x16x32_bf16 v[100:103], v[136:139], v[196:199], v[100:103]
	v_mfma_f32_16x16x32_bf16 v[92:95], v[128:131], v[218:221], v[92:95]
	v_mfma_f32_16x16x32_bf16 v[84:87], v[136:139], v[218:221], v[84:87]
	v_mfma_f32_16x16x32_bf16 v[76:79], v[128:131], v[226:229], v[76:79]
	v_mfma_f32_16x16x32_bf16 v[68:71], v[136:139], v[226:229], v[68:71]
	v_mfma_f32_16x16x32_bf16 v[124:127], v[132:135], v[192:195], v[124:127]
	v_mfma_f32_16x16x32_bf16 v[116:119], v[140:143], v[192:195], v[116:119]
	v_mfma_f32_16x16x32_bf16 v[108:111], v[132:135], v[214:217], v[108:111]
	v_mfma_f32_16x16x32_bf16 v[100:103], v[140:143], v[214:217], v[100:103]
	v_mfma_f32_16x16x32_bf16 v[92:95], v[132:135], v[222:225], v[92:95]
	v_mfma_f32_16x16x32_bf16 v[84:87], v[140:143], v[222:225], v[84:87]
	v_mfma_f32_16x16x32_bf16 v[76:79], v[132:135], v[230:233], v[76:79]
	v_mfma_f32_16x16x32_bf16 v[68:71], v[140:143], v[230:233], v[68:71]
	s_setprio 0
	s_setprio 1
	v_mfma_f32_16x16x32_bf16 v[120:123], v[156:159], v[188:191], v[120:123]
	v_mfma_f32_16x16x32_bf16 v[112:115], v[164:167], v[188:191], v[112:115]
	v_mfma_f32_16x16x32_bf16 v[104:107], v[156:159], v[196:199], v[104:107]
	v_mfma_f32_16x16x32_bf16 v[96:99], v[164:167], v[196:199], v[96:99]
	v_mfma_f32_16x16x32_bf16 v[88:91], v[156:159], v[218:221], v[88:91]
	v_mfma_f32_16x16x32_bf16 v[80:83], v[164:167], v[218:221], v[80:83]
	v_mfma_f32_16x16x32_bf16 v[72:75], v[156:159], v[226:229], v[72:75]
	v_mfma_f32_16x16x32_bf16 v[64:67], v[164:167], v[226:229], v[64:67]
	v_mfma_f32_16x16x32_bf16 v[120:123], v[160:163], v[192:195], v[120:123]
	v_mfma_f32_16x16x32_bf16 v[112:115], v[184:187], v[192:195], v[112:115]
	v_mfma_f32_16x16x32_bf16 v[104:107], v[160:163], v[214:217], v[104:107]
	v_mfma_f32_16x16x32_bf16 v[96:99], v[184:187], v[214:217], v[96:99]
	v_mfma_f32_16x16x32_bf16 v[88:91], v[160:163], v[222:225], v[88:91]
	v_mfma_f32_16x16x32_bf16 v[80:83], v[184:187], v[222:225], v[80:83]
	v_mfma_f32_16x16x32_bf16 v[72:75], v[160:163], v[230:233], v[72:75]
	v_mfma_f32_16x16x32_bf16 v[64:67], v[184:187], v[230:233], v[64:67]
	s_setprio 0
	s_barrier
	s_add_i32 s4, s54, s78
	v_lshl_add_u64 v[170:171], v[170:171], 0, s[64:65]
	s_mov_b32 m0, s4
	ds_read_b128 v[188:191], v175 offset:49152
	ds_read_b128 v[192:195], v175 offset:50176
	ds_read_b128 v[196:199], v175 offset:51200
	ds_read_b128 v[214:217], v175 offset:52224
	ds_read_b128 v[218:221], v175 offset:53248
	ds_read_b128 v[222:225], v175 offset:54272
	ds_read_b128 v[226:229], v175 offset:55296
	ds_read_b128 v[230:233], v175 offset:56320
	global_load_lds_dwordx4 v[170:171], off
	s_add_i32 m0, s4, 0x2000
	s_add_u32 s2, s2, 0x40080
	v_lshl_add_u64 v[170:171], v[200:201], 0, s[64:65]
	s_addc_u32 s3, s3, 0
	s_add_i32 s4, s58, s78
	global_load_lds_dwordx4 v[170:171], off
	v_lshl_add_u64 v[170:171], s[2:3], 0, v[146:147]
	s_mov_b32 m0, s4
	s_nop 0
	global_load_lds_dwordx4 v[170:171], off
	v_lshl_add_u64 v[170:171], s[2:3], 0, v[150:151]
	s_add_i32 m0, s4, 0x2000
	s_nop 0
	global_load_lds_dwordx4 v[170:171], off
	v_lshl_add_u64 v[170:171], v[234:235], 0, s[64:65]
	s_mov_b32 m0, s83
	s_nop 0
	global_load_lds_dwordx4 v[170:171], off
	v_lshl_add_u64 v[170:171], v[236:237], 0, s[64:65]
	s_mov_b32 m0, s84
	s_nop 0
	global_load_lds_dwordx4 v[170:171], off
	s_waitcnt vmcnt(8)
	s_waitcnt lgkmcnt(0)
	s_barrier
	s_setprio 1
	s_waitcnt lgkmcnt(0)
	v_mfma_f32_16x16x32_bf16 v[60:63], v[128:131], v[188:191], v[60:63]
	v_mfma_f32_16x16x32_bf16 v[52:55], v[136:139], v[188:191], v[52:55]
	v_mfma_f32_16x16x32_bf16 v[44:47], v[128:131], v[196:199], v[44:47]
	v_mfma_f32_16x16x32_bf16 v[36:39], v[136:139], v[196:199], v[36:39]
	v_mfma_f32_16x16x32_bf16 v[28:31], v[128:131], v[218:221], v[28:31]
	v_mfma_f32_16x16x32_bf16 v[20:23], v[136:139], v[218:221], v[20:23]
	v_mfma_f32_16x16x32_bf16 v[12:15], v[128:131], v[226:229], v[12:15]
	v_mfma_f32_16x16x32_bf16 v[4:7], v[136:139], v[226:229], v[4:7]
	v_mfma_f32_16x16x32_bf16 v[60:63], v[132:135], v[192:195], v[60:63]
	v_mfma_f32_16x16x32_bf16 v[52:55], v[140:143], v[192:195], v[52:55]
	v_mfma_f32_16x16x32_bf16 v[44:47], v[132:135], v[214:217], v[44:47]
	v_mfma_f32_16x16x32_bf16 v[36:39], v[140:143], v[214:217], v[36:39]
	v_mfma_f32_16x16x32_bf16 v[28:31], v[132:135], v[222:225], v[28:31]
	v_mfma_f32_16x16x32_bf16 v[20:23], v[140:143], v[222:225], v[20:23]
	v_mfma_f32_16x16x32_bf16 v[12:15], v[132:135], v[230:233], v[12:15]
	v_mfma_f32_16x16x32_bf16 v[4:7], v[140:143], v[230:233], v[4:7]
	s_setprio 0
	s_setprio 1
	v_mfma_f32_16x16x32_bf16 v[56:59], v[156:159], v[188:191], v[56:59]
	v_mfma_f32_16x16x32_bf16 v[48:51], v[164:167], v[188:191], v[48:51]
	v_mfma_f32_16x16x32_bf16 v[40:43], v[156:159], v[196:199], v[40:43]
	v_mfma_f32_16x16x32_bf16 v[32:35], v[164:167], v[196:199], v[32:35]
	v_mfma_f32_16x16x32_bf16 v[24:27], v[156:159], v[218:221], v[24:27]
	v_mfma_f32_16x16x32_bf16 v[16:19], v[164:167], v[218:221], v[16:19]
	v_mfma_f32_16x16x32_bf16 v[8:11], v[156:159], v[226:229], v[8:11]
	v_mfma_f32_16x16x32_bf16 v[0:3], v[164:167], v[226:229], v[0:3]
	v_mfma_f32_16x16x32_bf16 v[56:59], v[160:163], v[192:195], v[56:59]
	v_mfma_f32_16x16x32_bf16 v[48:51], v[184:187], v[192:195], v[48:51]
	v_mfma_f32_16x16x32_bf16 v[40:43], v[160:163], v[214:217], v[40:43]
	v_mfma_f32_16x16x32_bf16 v[32:35], v[184:187], v[214:217], v[32:35]
	v_mfma_f32_16x16x32_bf16 v[24:27], v[160:163], v[222:225], v[24:27]
	v_mfma_f32_16x16x32_bf16 v[16:19], v[184:187], v[222:225], v[16:19]
	v_mfma_f32_16x16x32_bf16 v[8:11], v[160:163], v[230:233], v[8:11]
	v_mfma_f32_16x16x32_bf16 v[0:3], v[184:187], v[230:233], v[0:3]
	s_setprio 0
	s_barrier
	s_add_i32 s37, s37, 2
	s_add_u32 s0, s0, 0x100
	s_addc_u32 s1, s1, 0
	s_add_u32 s9, s9, 0x100
	s_addc_u32 s36, s36, 0
	s_cmp_gt_u32 s37, 13
	s_cbranch_scc0 .LBB0_1084
	s_branch .Lpeel_exit_5

.LBB0_1136:
	s_add_u32 s44, s44, 0x80
	s_addc_u32 s45, s45, 0
	s_add_u32 s25, s42, 0x100
	s_addc_u32 s46, s43, 0
	s_mov_b32 s42, 0
	s_mov_b64 s[10:11], 0x80
	s_add_i32 s47, s42, 2
	s_add_u32 s58, s44, 0x80
	s_addc_u32 s43, s45, 0
	s_add_i32 s59, 0, 0x10000
	s_cmp_eq_u32 s85, s42
	s_cselect_b32 s43, s39, s43
	s_cselect_b32 s42, s38, s58
	v_add_u32_e32 v141, s59, v139
	s_cselect_b32 s93, s41, s46
	s_cselect_b32 s92, s40, s25
	s_add_i32 s58, 0, 0x14000
	ds_read_b128 v[142:145], v141
	ds_read_b128 v[146:149], v141 offset:1024
	ds_read_b128 v[150:153], v141 offset:2048
	ds_read_b128 v[154:157], v141 offset:3072
	v_add_u32_e32 v141, s58, v139
	ds_read_b128 v[158:161], v141
	ds_read_b128 v[162:165], v141 offset:1024
	ds_read_b128 v[166:169], v141 offset:2048
	ds_read_b128 v[170:173], v141 offset:3072
	v_lshl_add_u64 v[174:175], s[44:45], 0, v[134:135]
	s_add_i32 m0, s9, 0xc000
	ds_read_b128 v[184:187], v140
	ds_read_b128 v[188:191], v140 offset:1024
	ds_read_b128 v[192:195], v140 offset:2048
	ds_read_b128 v[196:199], v140 offset:3072
	ds_read_b128 v[214:217], v140 offset:4096
	ds_read_b128 v[218:221], v140 offset:5120
	ds_read_b128 v[222:225], v140 offset:6144
	ds_read_b128 v[226:229], v140 offset:7168
	global_load_lds_dwordx4 v[174:175], off
	v_lshl_add_u64 v[174:175], s[44:45], 0, v[136:137]
	s_add_i32 m0, s9, 0xe000
	s_nop 0
	global_load_lds_dwordx4 v[174:175], off
	s_waitcnt vmcnt(8)
	s_waitcnt lgkmcnt(0)
	s_barrier
	s_setprio 1
	s_waitcnt lgkmcnt(0)
	v_mfma_f32_16x16x32_bf16 v[124:127], v[142:145], v[184:187], 0
	v_mfma_f32_16x16x32_bf16 v[120:123], v[150:153], v[184:187], 0
	v_mfma_f32_16x16x32_bf16 v[116:119], v[142:145], v[192:195], 0
	v_mfma_f32_16x16x32_bf16 v[108:111], v[150:153], v[192:195], 0
	v_mfma_f32_16x16x32_bf16 v[100:103], v[142:145], v[214:217], 0
	v_mfma_f32_16x16x32_bf16 v[92:95], v[150:153], v[214:217], 0
	v_mfma_f32_16x16x32_bf16 v[84:87], v[142:145], v[222:225], 0
	v_mfma_f32_16x16x32_bf16 v[76:79], v[150:153], v[222:225], 0
	v_mfma_f32_16x16x32_bf16 v[124:127], v[146:149], v[188:191], v[124:127]
	v_mfma_f32_16x16x32_bf16 v[120:123], v[154:157], v[188:191], v[120:123]
	v_mfma_f32_16x16x32_bf16 v[116:119], v[146:149], v[196:199], v[116:119]
	v_mfma_f32_16x16x32_bf16 v[108:111], v[154:157], v[196:199], v[108:111]
	v_mfma_f32_16x16x32_bf16 v[100:103], v[146:149], v[218:221], v[100:103]
	v_mfma_f32_16x16x32_bf16 v[92:95], v[154:157], v[218:221], v[92:95]
	v_mfma_f32_16x16x32_bf16 v[84:87], v[146:149], v[226:229], v[84:87]
	v_mfma_f32_16x16x32_bf16 v[76:79], v[154:157], v[226:229], v[76:79]
	s_setprio 0
	s_setprio 1
	v_mfma_f32_16x16x32_bf16 v[112:115], v[158:161], v[184:187], 0
	v_mfma_f32_16x16x32_bf16 v[104:107], v[166:169], v[184:187], 0
	v_mfma_f32_16x16x32_bf16 v[96:99], v[158:161], v[192:195], 0
	v_mfma_f32_16x16x32_bf16 v[88:91], v[166:169], v[192:195], 0
	v_mfma_f32_16x16x32_bf16 v[80:83], v[158:161], v[214:217], 0
	v_mfma_f32_16x16x32_bf16 v[72:75], v[166:169], v[214:217], 0
	v_mfma_f32_16x16x32_bf16 v[68:71], v[158:161], v[222:225], 0
	v_mfma_f32_16x16x32_bf16 v[64:67], v[166:169], v[222:225], 0
	v_mfma_f32_16x16x32_bf16 v[112:115], v[162:165], v[188:191], v[112:115]
	v_mfma_f32_16x16x32_bf16 v[104:107], v[170:173], v[188:191], v[104:107]
	v_mfma_f32_16x16x32_bf16 v[96:99], v[162:165], v[196:199], v[96:99]
	v_mfma_f32_16x16x32_bf16 v[88:91], v[170:173], v[196:199], v[88:91]
	v_mfma_f32_16x16x32_bf16 v[80:83], v[162:165], v[218:221], v[80:83]
	v_mfma_f32_16x16x32_bf16 v[72:75], v[170:173], v[218:221], v[72:75]
	v_mfma_f32_16x16x32_bf16 v[68:71], v[162:165], v[226:229], v[68:71]
	v_mfma_f32_16x16x32_bf16 v[64:67], v[170:173], v[226:229], v[64:67]
	s_setprio 0
	s_barrier
	s_add_i32 s59, s59, s8
	v_lshl_add_u64 v[174:175], s[92:93], 0, v[176:177]
	s_mov_b32 m0, s59
	ds_read_b128 v[184:187], v140 offset:16384
	ds_read_b128 v[188:191], v140 offset:17408
	ds_read_b128 v[192:195], v140 offset:18432
	ds_read_b128 v[196:199], v140 offset:19456
	ds_read_b128 v[214:217], v140 offset:20480
	ds_read_b128 v[218:221], v140 offset:21504
	ds_read_b128 v[222:225], v140 offset:22528
	ds_read_b128 v[226:229], v140 offset:23552
	global_load_lds_dwordx4 v[174:175], off
	s_add_i32 m0, s59, 0x2000
	v_lshl_add_u64 v[200:201], s[92:93], 0, v[132:133]
	s_add_u32 s92, s92, s20
	s_addc_u32 s93, s93, s21
	s_add_i32 s58, s58, s8
	global_load_lds_dwordx4 v[200:201], off
	v_lshl_add_u64 v[230:231], s[92:93], 0, v[176:177]
	s_mov_b32 m0, s58
	v_lshl_add_u64 v[232:233], s[92:93], 0, v[132:133]
	global_load_lds_dwordx4 v[230:231], off
	s_add_i32 m0, s58, 0x2000
	v_lshl_add_u64 v[234:235], s[42:43], 0, v[128:129]
	global_load_lds_dwordx4 v[232:233], off
	s_mov_b32 m0, s9
	v_lshl_add_u64 v[236:237], s[42:43], 0, v[130:131]
	global_load_lds_dwordx4 v[234:235], off
	s_mov_b32 m0, s78
	s_nop 0
	global_load_lds_dwordx4 v[236:237], off
	s_waitcnt vmcnt(8)
	s_waitcnt lgkmcnt(0)
	s_barrier
	s_setprio 1
	s_waitcnt lgkmcnt(0)
	v_mfma_f32_16x16x32_bf16 v[60:63], v[142:145], v[184:187], 0
	v_mfma_f32_16x16x32_bf16 v[56:59], v[150:153], v[184:187], 0
	v_mfma_f32_16x16x32_bf16 v[52:55], v[142:145], v[192:195], 0
	v_mfma_f32_16x16x32_bf16 v[44:47], v[150:153], v[192:195], 0
	v_mfma_f32_16x16x32_bf16 v[36:39], v[142:145], v[214:217], 0
	v_mfma_f32_16x16x32_bf16 v[28:31], v[150:153], v[214:217], 0
	v_mfma_f32_16x16x32_bf16 v[20:23], v[142:145], v[222:225], 0
	v_mfma_f32_16x16x32_bf16 v[12:15], v[150:153], v[222:225], 0
	v_mfma_f32_16x16x32_bf16 v[60:63], v[146:149], v[188:191], v[60:63]
	v_mfma_f32_16x16x32_bf16 v[56:59], v[154:157], v[188:191], v[56:59]
	v_mfma_f32_16x16x32_bf16 v[52:55], v[146:149], v[196:199], v[52:55]
	v_mfma_f32_16x16x32_bf16 v[44:47], v[154:157], v[196:199], v[44:47]
	v_mfma_f32_16x16x32_bf16 v[36:39], v[146:149], v[218:221], v[36:39]
	v_mfma_f32_16x16x32_bf16 v[28:31], v[154:157], v[218:221], v[28:31]
	v_mfma_f32_16x16x32_bf16 v[20:23], v[146:149], v[226:229], v[20:23]
	v_mfma_f32_16x16x32_bf16 v[12:15], v[154:157], v[226:229], v[12:15]
	s_setprio 0
	s_setprio 1
	v_mfma_f32_16x16x32_bf16 v[48:51], v[158:161], v[184:187], 0
	v_mfma_f32_16x16x32_bf16 v[40:43], v[166:169], v[184:187], 0
	v_mfma_f32_16x16x32_bf16 v[32:35], v[158:161], v[192:195], 0
	v_mfma_f32_16x16x32_bf16 v[24:27], v[166:169], v[192:195], 0
	v_mfma_f32_16x16x32_bf16 v[16:19], v[158:161], v[214:217], 0
	v_mfma_f32_16x16x32_bf16 v[8:11], v[166:169], v[214:217], 0
	v_mfma_f32_16x16x32_bf16 v[4:7], v[158:161], v[222:225], 0
	v_mfma_f32_16x16x32_bf16 v[0:3], v[166:169], v[222:225], 0
	v_mfma_f32_16x16x32_bf16 v[48:51], v[162:165], v[188:191], v[48:51]
	v_mfma_f32_16x16x32_bf16 v[40:43], v[170:173], v[188:191], v[40:43]
	v_mfma_f32_16x16x32_bf16 v[32:35], v[162:165], v[196:199], v[32:35]
	v_mfma_f32_16x16x32_bf16 v[24:27], v[170:173], v[196:199], v[24:27]
	v_mfma_f32_16x16x32_bf16 v[16:19], v[162:165], v[218:221], v[16:19]
	v_mfma_f32_16x16x32_bf16 v[8:11], v[170:173], v[218:221], v[8:11]
	v_mfma_f32_16x16x32_bf16 v[4:7], v[162:165], v[226:229], v[4:7]
	v_mfma_f32_16x16x32_bf16 v[0:3], v[170:173], v[226:229], v[0:3]
	s_setprio 0
	s_barrier
	s_add_i32 s58, 0, 0x18000
	v_add_u32_e32 v141, s58, v139
	s_add_i32 s59, 0, 0x1c000
	ds_read_b128 v[142:145], v141
	ds_read_b128 v[146:149], v141 offset:1024
	ds_read_b128 v[150:153], v141 offset:2048
	ds_read_b128 v[154:157], v141 offset:3072
	v_add_u32_e32 v141, s59, v139
	ds_read_b128 v[158:161], v141
	ds_read_b128 v[162:165], v141 offset:1024
	ds_read_b128 v[166:169], v141 offset:2048
	ds_read_b128 v[170:173], v141 offset:3072
	s_add_u32 s42, s42, s22
	s_addc_u32 s43, s43, s23
	s_mov_b32 m0, s79
	v_lshl_add_u64 v[238:239], s[42:43], 0, v[128:129]
	ds_read_b128 v[184:187], v140 offset:32768
	ds_read_b128 v[188:191], v140 offset:33792
	ds_read_b128 v[192:195], v140 offset:34816
	ds_read_b128 v[196:199], v140 offset:35840
	ds_read_b128 v[214:217], v140 offset:36864
	ds_read_b128 v[218:221], v140 offset:37888
	ds_read_b128 v[222:225], v140 offset:38912
	ds_read_b128 v[226:229], v140 offset:39936
	global_load_lds_dwordx4 v[238:239], off
	v_lshl_add_u64 v[238:239], s[42:43], 0, v[130:131]
	s_mov_b32 m0, s80
	s_nop 0
	global_load_lds_dwordx4 v[238:239], off
	s_waitcnt vmcnt(8)
	s_waitcnt lgkmcnt(0)
	s_barrier
	s_setprio 1
	s_waitcnt lgkmcnt(0)
	v_mfma_f32_16x16x32_bf16 v[124:127], v[142:145], v[184:187], v[124:127]
	v_mfma_f32_16x16x32_bf16 v[120:123], v[150:153], v[184:187], v[120:123]
	v_mfma_f32_16x16x32_bf16 v[116:119], v[142:145], v[192:195], v[116:119]
	v_mfma_f32_16x16x32_bf16 v[108:111], v[150:153], v[192:195], v[108:111]
	v_mfma_f32_16x16x32_bf16 v[100:103], v[142:145], v[214:217], v[100:103]
	v_mfma_f32_16x16x32_bf16 v[92:95], v[150:153], v[214:217], v[92:95]
	v_mfma_f32_16x16x32_bf16 v[84:87], v[142:145], v[222:225], v[84:87]
	v_mfma_f32_16x16x32_bf16 v[76:79], v[150:153], v[222:225], v[76:79]
	v_mfma_f32_16x16x32_bf16 v[124:127], v[146:149], v[188:191], v[124:127]
	v_mfma_f32_16x16x32_bf16 v[120:123], v[154:157], v[188:191], v[120:123]
	v_mfma_f32_16x16x32_bf16 v[116:119], v[146:149], v[196:199], v[116:119]
	v_mfma_f32_16x16x32_bf16 v[108:111], v[154:157], v[196:199], v[108:111]
	v_mfma_f32_16x16x32_bf16 v[100:103], v[146:149], v[218:221], v[100:103]
	v_mfma_f32_16x16x32_bf16 v[92:95], v[154:157], v[218:221], v[92:95]
	v_mfma_f32_16x16x32_bf16 v[84:87], v[146:149], v[226:229], v[84:87]
	v_mfma_f32_16x16x32_bf16 v[76:79], v[154:157], v[226:229], v[76:79]
	s_setprio 0
	s_setprio 1
	v_mfma_f32_16x16x32_bf16 v[112:115], v[158:161], v[184:187], v[112:115]
	v_mfma_f32_16x16x32_bf16 v[104:107], v[166:169], v[184:187], v[104:107]
	v_mfma_f32_16x16x32_bf16 v[96:99], v[158:161], v[192:195], v[96:99]
	v_mfma_f32_16x16x32_bf16 v[88:91], v[166:169], v[192:195], v[88:91]
	v_mfma_f32_16x16x32_bf16 v[80:83], v[158:161], v[214:217], v[80:83]
	v_mfma_f32_16x16x32_bf16 v[72:75], v[166:169], v[214:217], v[72:75]
	v_mfma_f32_16x16x32_bf16 v[68:71], v[158:161], v[222:225], v[68:71]
	v_mfma_f32_16x16x32_bf16 v[64:67], v[166:169], v[222:225], v[64:67]
	v_mfma_f32_16x16x32_bf16 v[112:115], v[162:165], v[188:191], v[112:115]
	v_mfma_f32_16x16x32_bf16 v[104:107], v[170:173], v[188:191], v[104:107]
	v_mfma_f32_16x16x32_bf16 v[96:99], v[162:165], v[196:199], v[96:99]
	v_mfma_f32_16x16x32_bf16 v[88:91], v[170:173], v[196:199], v[88:91]
	v_mfma_f32_16x16x32_bf16 v[80:83], v[162:165], v[218:221], v[80:83]
	v_mfma_f32_16x16x32_bf16 v[72:75], v[170:173], v[218:221], v[72:75]
	v_mfma_f32_16x16x32_bf16 v[68:71], v[162:165], v[226:229], v[68:71]
	v_mfma_f32_16x16x32_bf16 v[64:67], v[170:173], v[226:229], v[64:67]
	s_setprio 0
	s_barrier
	s_add_i32 s42, s58, s8
	v_lshl_add_u64 v[174:175], v[174:175], 0, s[10:11]
	s_mov_b32 m0, s42
	ds_read_b128 v[184:187], v140 offset:49152
	ds_read_b128 v[188:191], v140 offset:50176
	ds_read_b128 v[192:195], v140 offset:51200
	ds_read_b128 v[196:199], v140 offset:52224
	ds_read_b128 v[214:217], v140 offset:53248
	ds_read_b128 v[218:221], v140 offset:54272
	ds_read_b128 v[222:225], v140 offset:55296
	ds_read_b128 v[226:229], v140 offset:56320
	global_load_lds_dwordx4 v[174:175], off
	v_lshl_add_u64 v[174:175], v[200:201], 0, s[10:11]
	s_add_i32 m0, s42, 0x2000
	s_add_i32 s42, s59, s8
	global_load_lds_dwordx4 v[174:175], off
	v_lshl_add_u64 v[174:175], v[230:231], 0, s[10:11]
	s_mov_b32 m0, s42
	s_nop 0
	global_load_lds_dwordx4 v[174:175], off
	v_lshl_add_u64 v[174:175], v[232:233], 0, s[10:11]
	s_add_i32 m0, s42, 0x2000
	s_nop 0
	global_load_lds_dwordx4 v[174:175], off
	v_lshl_add_u64 v[174:175], v[234:235], 0, s[10:11]
	s_mov_b32 m0, s83
	s_nop 0
	global_load_lds_dwordx4 v[174:175], off
	v_lshl_add_u64 v[174:175], v[236:237], 0, s[10:11]
	s_mov_b32 m0, s84
	s_nop 0
	global_load_lds_dwordx4 v[174:175], off
	s_waitcnt vmcnt(8)
	s_waitcnt lgkmcnt(0)
	s_barrier
	s_setprio 1
	s_waitcnt lgkmcnt(0)
	v_mfma_f32_16x16x32_bf16 v[60:63], v[142:145], v[184:187], v[60:63]
	v_mfma_f32_16x16x32_bf16 v[56:59], v[150:153], v[184:187], v[56:59]
	v_mfma_f32_16x16x32_bf16 v[52:55], v[142:145], v[192:195], v[52:55]
	v_mfma_f32_16x16x32_bf16 v[44:47], v[150:153], v[192:195], v[44:47]
	v_mfma_f32_16x16x32_bf16 v[36:39], v[142:145], v[214:217], v[36:39]
	v_mfma_f32_16x16x32_bf16 v[28:31], v[150:153], v[214:217], v[28:31]
	v_mfma_f32_16x16x32_bf16 v[20:23], v[142:145], v[222:225], v[20:23]
	v_mfma_f32_16x16x32_bf16 v[12:15], v[150:153], v[222:225], v[12:15]
	v_mfma_f32_16x16x32_bf16 v[60:63], v[146:149], v[188:191], v[60:63]
	v_mfma_f32_16x16x32_bf16 v[56:59], v[154:157], v[188:191], v[56:59]
	v_mfma_f32_16x16x32_bf16 v[52:55], v[146:149], v[196:199], v[52:55]
	v_mfma_f32_16x16x32_bf16 v[44:47], v[154:157], v[196:199], v[44:47]
	v_mfma_f32_16x16x32_bf16 v[36:39], v[146:149], v[218:221], v[36:39]
	v_mfma_f32_16x16x32_bf16 v[28:31], v[154:157], v[218:221], v[28:31]
	v_mfma_f32_16x16x32_bf16 v[20:23], v[146:149], v[226:229], v[20:23]
	v_mfma_f32_16x16x32_bf16 v[12:15], v[154:157], v[226:229], v[12:15]
	s_setprio 0
	s_setprio 1
	v_mfma_f32_16x16x32_bf16 v[48:51], v[158:161], v[184:187], v[48:51]
	v_mfma_f32_16x16x32_bf16 v[40:43], v[166:169], v[184:187], v[40:43]
	v_mfma_f32_16x16x32_bf16 v[32:35], v[158:161], v[192:195], v[32:35]
	v_mfma_f32_16x16x32_bf16 v[24:27], v[166:169], v[192:195], v[24:27]
	v_mfma_f32_16x16x32_bf16 v[16:19], v[158:161], v[214:217], v[16:19]
	v_mfma_f32_16x16x32_bf16 v[8:11], v[166:169], v[214:217], v[8:11]
	v_mfma_f32_16x16x32_bf16 v[4:7], v[158:161], v[222:225], v[4:7]
	v_mfma_f32_16x16x32_bf16 v[0:3], v[166:169], v[222:225], v[0:3]
	v_mfma_f32_16x16x32_bf16 v[48:51], v[162:165], v[188:191], v[48:51]
	v_mfma_f32_16x16x32_bf16 v[40:43], v[170:173], v[188:191], v[40:43]
	v_mfma_f32_16x16x32_bf16 v[32:35], v[162:165], v[196:199], v[32:35]
	v_mfma_f32_16x16x32_bf16 v[24:27], v[170:173], v[196:199], v[24:27]
	v_mfma_f32_16x16x32_bf16 v[16:19], v[162:165], v[218:221], v[16:19]
	v_mfma_f32_16x16x32_bf16 v[8:11], v[170:173], v[218:221], v[8:11]
	v_mfma_f32_16x16x32_bf16 v[4:7], v[162:165], v[226:229], v[4:7]
	v_mfma_f32_16x16x32_bf16 v[0:3], v[170:173], v[226:229], v[0:3]
	s_setprio 0
	s_barrier
	s_add_u32 s44, s44, 0x100
	s_addc_u32 s45, s45, 0
	s_add_u32 s25, s25, 0x100
	s_addc_u32 s46, s46, 0
	s_cmp_ge_u32 s47, s77
	s_mov_b32 s42, s47
	s_cbranch_scc0 .LBB0_1137
	s_branch .Lpeel_exit_6
